# SWA task: K-fragment and V-fragment LDS reads hoisted ahead of their MFMAs; scan: sigmoid bias add + scale fused into one fma
# speedup vs baseline: 1.0111x; 1.0039x over previous
.LBB0_558:
	s_cmpk_gt_i32 s2, 0xbf
	s_cbranch_scc1 .LBB0_569
	s_ashr_i32 s8, s22, 6
	s_movk_i32 s3, 0x400
	s_waitcnt vmcnt(0)
	v_lshlrev_b32_e32 v0, 2, v213
	v_lshrrev_b32_e32 v4, 1, v213
	v_cmp_gt_i32_e64 s[4:5], s3, v213
	s_mul_i32 s3, s8, 0x2200
	v_and_b32_e32 v0, 16, v0
	v_and_b32_e32 v3, 3, v213
	v_and_b32_e32 v4, 12, v4
	s_add_i32 s9, s3, 0
	s_and_b32 s3, s22, 0xffffffc0
	v_and_b32_e32 v1, 63, v213
	v_and_b32_e32 v101, 31, v213
	v_bfe_u32 v2, v213, 5, 1
	v_or3_b32 v3, v3, v0, v4
	v_and_b32_e32 v4, 15, v213
	s_ashr_i32 s28, s3, 31
	v_bfe_u32 v100, v213, 4, 2
	v_lshlrev_b32_e32 v0, 3, v4
	v_lshlrev_b32_e32 v104, 4, v2
	v_lshlrev_b32_e32 v4, 4, v4
	s_movk_i32 s29, 0x110
	v_mul_u32_u24_e32 v7, 0x110, v101
	v_cmp_gt_u32_e64 s[6:7], 32, v1
	s_cmp_lt_u32 s22, 64
	v_mul_i32_i24_e32 v1, 0xfffffef8, v101
	v_mov_b32_e32 v102, 0
	v_add_u32_e32 v5, s9, v4
	v_add_u32_e32 v6, s9, v104
	v_mul_u32_u24_e32 v3, 0x110, v3
	v_mad_u32_u24 v105, v101, s29, 0
	s_cselect_b64 s[12:13], -1, 0
	v_lshl_or_b32 v107, s8, 2, v2
	v_add_u32_e32 v106, 0, v4
	s_movk_i32 s10, 0xfef8
	v_mul_u32_u24_e32 v4, 0x110, v100
	s_lshl_b32 s30, s8, 10
	s_movk_i32 s8, 0x1100
	v_mov_b32_e32 v8, s9
	v_add3_u32 v1, v7, v1, 0
	s_mov_b32 s11, 0
	v_or_b32_e32 v214, 2, v107
	v_mad_i32_i24 v215, v101, s10, v105
	v_lshlrev_b32_e32 v216, 8, v2
	v_mad_u32_u24 v217, v2, s8, v8
	v_add_u32_e32 v218, 0x4400, v1
	v_mov_b32_e32 v219, s0
	v_mov_b32_e32 v220, s1
	v_lshlrev_b32_e32 v108, 1, v0
	v_mov_b32_e32 v109, v102
	s_movk_i32 s31, 0x1ff
	s_mov_b32 s34, 0x2f20000
	s_movk_i32 s35, 0x600
	v_mov_b32_e32 v221, 0x600
	s_mov_b64 s[14:15], 0x14000000
	s_brev_b32 s36, 40
	s_mov_b32 s37, 0x14001000
	s_mov_b32 s38, 0x14003000
	s_mov_b32 s39, 0x14004000
	s_mov_b32 s40, 0x14006000
	s_mov_b32 s41, 0x14007000
	s_mov_b32 s42, 0x14009000
	s_mov_b32 s43, 0x1400a000
	s_mov_b32 s44, 0x1400c000
	s_mov_b32 s45, 0x1400d000
	s_mov_b32 s46, 0x1400f000
	s_mov_b32 s47, 0x14010000
	s_mov_b32 s48, 0x14012000
	s_mov_b32 s49, 0x14013000
	s_mov_b32 s50, 0x14015000
	s_mov_b64 s[16:17], 0x17000000
	s_mov_b64 s[18:19], 0x1b000000
	s_movk_i32 s51, 0x2000
	v_add_u32_e32 v222, v5, v4
	s_movk_i32 s52, 0x1000
	s_movk_i32 s53, 0x3000
	s_movk_i32 s54, 0x4000
	s_movk_i32 s55, 0x6000
	s_movk_i32 s56, 0x7000
	s_mov_b32 s57, 0x9000
	s_mov_b32 s58, 0xa000
	v_add_u32_e32 v223, v6, v3
	s_mov_b32 s59, 0xbfb8aa3b
	v_mov_b32_e32 v224, 0x260
	s_mov_b32 s60, 0xc000
	s_mov_b32 s61, 0xd000
	s_mov_b32 s62, 0xf000
	s_mov_b32 s63, 0x10000
	s_mov_b32 s64, 0x12000
	s_mov_b32 s65, 0x13000
	s_mov_b32 s66, 0x15000
	s_mov_b32 s67, 0x16000
	s_movk_i32 s68, 0x5000
	s_mov_b32 s69, 0x11000
	s_mov_b32 s70, 0x14000
	s_mov_b32 s71, s2

.LBB0_564:
	s_add_i32 s22, s23, 1
	s_lshl_b32 s8, s22, 9
	s_cmp_lg_u32 s23, 7
	s_cselect_b32 s8, s8, 0xe00
	s_mul_i32 s10, s8, 0x300
	s_ashr_i32 s9, s10, 31
	s_mov_b32 s8, s10
	v_lshl_add_u64 v[84:85], s[8:9], 1, v[110:111]
	v_add_co_u32_e32 v2, vcc, s52, v84
	s_waitcnt vmcnt(15)
	ds_write_b128 v222, v[32:35] offset:33792
	s_waitcnt vmcnt(14)
	ds_write_b128 v222, v[36:39] offset:34880
	s_waitcnt vmcnt(13)
	ds_write_b128 v222, v[40:43] offset:35968
	s_waitcnt vmcnt(12)
	ds_write_b128 v222, v[44:47] offset:37056
	s_waitcnt vmcnt(11)
	ds_write_b128 v222, v[48:51] offset:38144
	s_waitcnt vmcnt(10)
	ds_write_b128 v222, v[56:59] offset:39232
	s_waitcnt vmcnt(9)
	ds_write_b128 v222, v[64:67] offset:40320
	s_waitcnt vmcnt(8)
	v_mul_f32_e32 v242, 0xbfb8aa3b, v225
	v_mul_f32_e32 v243, 0xbfb8aa3b, v226
	ds_write_b128 v222, v[72:75] offset:41408
	v_lshl_add_u64 v[0:1], s[10:11], 1, v[110:111]
	v_addc_co_u32_e32 v3, vcc, 0, v85, vcc
	global_load_dwordx4 v[32:35], v[0:1], off
	global_load_dwordx4 v[36:39], v[2:3], off offset:2048
	v_add_co_u32_e32 v0, vcc, s53, v84
	v_add_u32_e32 v86, v105, v104
	s_nop 0
	v_addc_co_u32_e32 v1, vcc, 0, v85, vcc
	v_add_co_u32_e32 v2, vcc, s54, v84
	s_lshl_b32 s8, s23, 13
	s_nop 0
	v_addc_co_u32_e32 v3, vcc, 0, v85, vcc
	global_load_dwordx4 v[40:43], v[0:1], off
	global_load_dwordx4 v[44:47], v[2:3], off offset:2048
	v_add_co_u32_e32 v0, vcc, s55, v84
	s_and_b32 s10, s8, 0x2000
	s_nop 0
	v_addc_co_u32_e32 v1, vcc, 0, v85, vcc
	v_add_co_u32_e32 v2, vcc, s56, v84
	s_cmp_eq_u32 s23, 0
	s_nop 0
	v_addc_co_u32_e32 v3, vcc, 0, v85, vcc
	global_load_dwordx4 v[48:51], v[0:1], off
	global_load_dwordx4 v[56:59], v[2:3], off offset:2048
	v_add_co_u32_e32 v0, vcc, s57, v84
	s_nop 1
	v_addc_co_u32_e32 v1, vcc, 0, v85, vcc
	v_add_co_u32_e32 v2, vcc, s58, v84
	s_nop 1
	v_addc_co_u32_e32 v3, vcc, 0, v85, vcc
	global_load_dwordx4 v[64:67], v[0:1], off
	global_load_dwordx4 v[72:75], v[2:3], off offset:2048
	s_waitcnt lgkmcnt(0)
	ds_read_b128 v[0:3], v223 offset:33792
	ds_read_b128 v[4:7], v86
	ds_read_b128 v[116:119], v223 offset:33824
	ds_read_b128 v[120:123], v86 offset:32
	s_waitcnt lgkmcnt(2)
	v_mfma_f32_32x32x16_bf16 v[16:31], v[0:3], v[4:7], 0
	ds_read_b128 v[4:7], v86 offset:8704
	ds_read_b128 v[124:127], v86 offset:8736
	s_waitcnt lgkmcnt(1)
	v_mfma_f32_32x32x16_bf16 v[0:15], v[0:3], v[4:7], 0
	v_mfma_f32_32x32x16_bf16 v[16:31], v[116:119], v[120:123], v[16:31]
	s_waitcnt lgkmcnt(0)
	v_mfma_f32_32x32x16_bf16 v[0:15], v[116:119], v[124:127], v[0:15]
	ds_read_b128 v[116:119], v223 offset:33856
	ds_read_b128 v[120:123], v86 offset:64
	ds_read_b128 v[124:127], v223 offset:33888
	ds_read_b128 v[128:131], v86 offset:96
	s_waitcnt lgkmcnt(2)
	v_mfma_f32_32x32x16_bf16 v[16:31], v[116:119], v[120:123], v[16:31]
	ds_read_b128 v[120:123], v86 offset:8768
	ds_read_b128 v[132:135], v86 offset:8800
	s_waitcnt lgkmcnt(1)
	v_mfma_f32_32x32x16_bf16 v[0:15], v[116:119], v[120:123], v[0:15]
	v_mfma_f32_32x32x16_bf16 v[16:31], v[124:127], v[128:131], v[16:31]
	s_waitcnt lgkmcnt(0)
	v_mfma_f32_32x32x16_bf16 v[0:15], v[124:127], v[132:135], v[0:15]
	ds_read_b128 v[116:119], v223 offset:33920
	ds_read_b128 v[120:123], v86 offset:128
	ds_read_b128 v[124:127], v223 offset:33952
	ds_read_b128 v[128:131], v86 offset:160
	s_waitcnt lgkmcnt(2)
	v_mfma_f32_32x32x16_bf16 v[16:31], v[116:119], v[120:123], v[16:31]
	ds_read_b128 v[120:123], v86 offset:8832
	ds_read_b128 v[132:135], v86 offset:8864
	s_waitcnt lgkmcnt(1)
	v_mfma_f32_32x32x16_bf16 v[0:15], v[116:119], v[120:123], v[0:15]
	v_mfma_f32_32x32x16_bf16 v[16:31], v[124:127], v[128:131], v[16:31]
	s_waitcnt lgkmcnt(0)
	v_mfma_f32_32x32x16_bf16 v[0:15], v[124:127], v[132:135], v[0:15]
	ds_read_b128 v[116:119], v223 offset:33984
	ds_read_b128 v[120:123], v86 offset:192
	ds_read_b128 v[124:127], v223 offset:34016
	ds_read_b128 v[128:131], v86 offset:224
	s_waitcnt lgkmcnt(2)
	v_mfma_f32_32x32x16_bf16 v[16:31], v[116:119], v[120:123], v[16:31]
	ds_read_b128 v[120:123], v86 offset:8896
	s_waitcnt lgkmcnt(1)
	v_mfma_f32_32x32x16_bf16 v[16:31], v[124:127], v[128:131], v[16:31]
	ds_read_b128 v[128:131], v86 offset:8928
	s_waitcnt lgkmcnt(1)
	v_mfma_f32_32x32x16_bf16 v[0:15], v[116:119], v[120:123], v[0:15]
	s_nop 8
	v_fma_f32 v16, v16, s59, v242
	v_exp_f32_e32 v16, v16
	v_fma_f32 v17, v17, s59, v242
	v_exp_f32_e32 v17, v17
	v_add_f32_e32 v16, 1.0, v16
	v_rcp_f32_e32 v16, v16
	s_waitcnt lgkmcnt(0)
	v_mfma_f32_32x32x16_bf16 v[0:15], v[124:127], v[128:131], v[0:15]
	v_fma_f32 v18, v18, s59, v242
	v_mul_f32_e32 v16, v227, v16
	v_exp_f32_e32 v116, v16
	v_exp_f32_e32 v18, v18
	v_fma_f32 v19, v19, s59, v242
	v_fma_f32 v16, -v116, v116, 1.0
	s_nop 1
	s_nop 1
	s_nop 1
	v_fma_f32 v0, v0, s59, v243
	v_exp_f32_e32 v0, v0
	v_fma_f32 v2, v2, s59, v243
	v_add_f32_e32 v0, 1.0, v0
	v_rcp_f32_e32 v0, v0
	v_exp_f32_e32 v2, v2
	s_cselect_b64 s[8:9], -1, 0
	s_and_b64 s[8:9], s[8:9], s[6:7]
	s_and_b64 s[8:9], s[8:9], s[12:13]
	v_sqrt_f32_e32 v16, v16
	s_nop 0
	v_cndmask_b32_e64 v16, v16, 1.0, s[8:9]
	v_mul_f32_e32 v117, v0, v16
	v_add_f32_e32 v0, 1.0, v17
	v_rcp_f32_e32 v0, v0
	ds_read_u16 v16, v228 offset:33792
	ds_read_u16 v17, v228 offset:34064
	ds_read_u16 v125, v228 offset:34336
	ds_read_u16 v129, v228 offset:34608
	ds_read_u16 v133, v228 offset:34880
	ds_read_u16 v137, v228 offset:35152
	ds_read_u16 v141, v228 offset:35424
	ds_read_u16 v145, v228 offset:35696
	s_waitcnt lgkmcnt(7)
	v_lshlrev_b32_e32 v103, 16, v16
	v_pk_mul_f32 v[120:121], v[116:117], v[102:103]
	v_mul_f32_e32 v0, v227, v0
	v_exp_f32_e32 v118, v0
	v_fma_f32 v0, v1, s59, v243
	v_exp_f32_e32 v0, v0
	v_fma_f32 v1, -v118, v118, 1.0
	v_add_f32_e32 v0, 1.0, v0
	v_rcp_f32_e32 v0, v0
	v_add_f32_e32 v2, 1.0, v2
	v_rcp_f32_e32 v2, v2
	v_exp_f32_e32 v19, v19
	s_waitcnt lgkmcnt(5)
	v_lshlrev_b32_e32 v125, 16, v125
	s_waitcnt lgkmcnt(4)
	v_lshlrev_b32_e32 v129, 16, v129
	s_waitcnt lgkmcnt(3)
	v_lshlrev_b32_e32 v133, 16, v133
	v_lshlrev_b32_e32 v119, 16, v17
	s_waitcnt lgkmcnt(2)
	v_lshlrev_b32_e32 v137, 16, v137
	v_sqrt_f32_e32 v1, v1
	s_nop 0
	v_mul_f32_e32 v16, v0, v1
	v_add_f32_e32 v0, 1.0, v18
	v_rcp_f32_e32 v17, v0
	v_pk_fma_f32 v[0:1], v[116:117], v[102:103], v[120:121] op_sel:[0,0,1] op_sel_hi:[1,1,0]
	v_mul_f32_e32 v18, v116, v118
	v_mov_b32_e32 v1, v16
	v_mul_f32_e32 v16, v227, v17
	v_exp_f32_e32 v124, v16
	v_pk_mul_f32 v[122:123], v[0:1], v[118:119]
	s_waitcnt lgkmcnt(1)
	v_lshlrev_b32_e32 v141, 16, v141
	v_pk_fma_f32 v[0:1], v[0:1], v[118:119], v[122:123] op_sel:[0,0,1] op_sel_hi:[1,1,0]
	v_fma_f32 v16, -v124, v124, 1.0
	s_waitcnt lgkmcnt(0)
	v_lshlrev_b32_e32 v145, 16, v145
	s_nop 0
	s_nop 0
	s_nop 1
	s_nop 1
	v_sqrt_f32_e32 v16, v16
	s_nop 0
	v_mul_f32_e32 v2, v2, v16
	v_add_f32_e32 v16, 1.0, v19
	v_rcp_f32_e32 v16, v16
	v_mov_b32_e32 v1, v2
	v_mul_f32_e32 v17, v18, v124
	v_pk_mul_f32 v[126:127], v[0:1], v[124:125]
	v_mul_f32_e32 v2, v227, v16
	v_exp_f32_e32 v128, v2
	v_fma_f32 v2, v3, s59, v243
	v_exp_f32_e32 v2, v2
	v_fma_f32 v3, -v128, v128, 1.0
	v_add_f32_e32 v2, 1.0, v2
	v_rcp_f32_e32 v2, v2
	v_pk_fma_f32 v[0:1], v[0:1], v[124:125], v[126:127] op_sel:[0,0,1] op_sel_hi:[1,1,0]
	s_nop 0
	s_nop 1
	v_fma_f32 v18, v20, s59, v242
	v_exp_f32_e32 v18, v18
	s_nop 1
	v_sqrt_f32_e32 v3, v3
	s_nop 0
	v_mul_f32_e32 v2, v2, v3
	v_add_f32_e32 v3, 1.0, v18
	v_rcp_f32_e32 v3, v3
	v_mov_b32_e32 v1, v2
	v_mul_f32_e32 v16, v17, v128
	v_pk_mul_f32 v[130:131], v[0:1], v[128:129]
	v_mul_f32_e32 v2, v227, v3
	v_exp_f32_e32 v132, v2
	v_fma_f32 v2, v4, s59, v243
	v_exp_f32_e32 v2, v2
	v_fma_f32 v3, -v132, v132, 1.0
	v_add_f32_e32 v2, 1.0, v2
	v_rcp_f32_e32 v2, v2
	v_pk_fma_f32 v[0:1], v[0:1], v[128:129], v[130:131] op_sel:[0,0,1] op_sel_hi:[1,1,0]
	s_nop 0
	s_nop 1
	v_fma_f32 v17, v21, s59, v242
	v_exp_f32_e32 v17, v17
	s_nop 1
	v_sqrt_f32_e32 v3, v3
	s_nop 0
	v_mul_f32_e32 v2, v2, v3
	v_add_f32_e32 v3, 1.0, v17
	v_rcp_f32_e32 v3, v3
	v_mov_b32_e32 v1, v2
	v_pk_mul_f32 v[134:135], v[0:1], v[132:133]
	v_mul_f32_e32 v2, v227, v3
	v_exp_f32_e32 v136, v2
	v_fma_f32 v2, v5, s59, v243
	v_mul_f32_e32 v5, v16, v132
	v_fma_f32 v3, -v136, v136, 1.0
	v_exp_f32_e32 v2, v2
	v_pk_fma_f32 v[0:1], v[0:1], v[132:133], v[134:135] op_sel:[0,0,1] op_sel_hi:[1,1,0]
	v_add_f32_e32 v2, 1.0, v2
	v_rcp_f32_e32 v2, v2
	v_mul_f32_e32 v5, v5, v136
	s_nop 0
	s_nop 1
	v_fma_f32 v16, v22, s59, v242
	v_exp_f32_e32 v16, v16
	s_nop 1
	v_sqrt_f32_e32 v3, v3
	s_nop 0
	v_mul_f32_e32 v2, v2, v3
	v_add_f32_e32 v3, 1.0, v16
	v_rcp_f32_e32 v3, v3
	v_mov_b32_e32 v1, v2
	v_pk_mul_f32 v[138:139], v[0:1], v[136:137]
	v_mul_f32_e32 v2, v227, v3
	v_exp_f32_e32 v140, v2
	v_fma_f32 v2, v6, s59, v243
	v_exp_f32_e32 v2, v2
	v_fma_f32 v3, -v140, v140, 1.0
	v_add_f32_e32 v2, 1.0, v2
	v_rcp_f32_e32 v2, v2
	v_pk_fma_f32 v[0:1], v[0:1], v[136:137], v[138:139] op_sel:[0,0,1] op_sel_hi:[1,1,0]
	v_mul_f32_e32 v5, v5, v140
	s_nop 0
	s_nop 1
	v_fma_f32 v6, v23, s59, v242
	v_exp_f32_e32 v6, v6
	s_nop 1
	v_sqrt_f32_e32 v3, v3
	s_nop 0
	v_mul_f32_e32 v2, v2, v3
	v_add_f32_e32 v3, 1.0, v6
	v_rcp_f32_e32 v3, v3
	v_mov_b32_e32 v1, v2
	v_pk_mul_f32 v[142:143], v[0:1], v[140:141]
	v_mul_f32_e32 v2, v227, v3
	v_exp_f32_e32 v144, v2
	v_fma_f32 v2, v7, s59, v243
	v_exp_f32_e32 v2, v2
	v_fma_f32 v3, -v144, v144, 1.0
	v_add_f32_e32 v2, 1.0, v2
	v_rcp_f32_e32 v2, v2
	v_pk_fma_f32 v[0:1], v[0:1], v[140:141], v[142:143] op_sel:[0,0,1] op_sel_hi:[1,1,0]
	v_mul_f32_e32 v5, v5, v144
	v_mov_b32_e32 v142, 0
	s_nop 0
	s_nop 1
	v_fma_f32 v6, v24, s59, v242
	v_exp_f32_e32 v6, v6
	s_nop 1
	v_sqrt_f32_e32 v3, v3
	s_nop 0
	v_mul_f32_e32 v2, v2, v3
	v_add_f32_e32 v3, 1.0, v6
	v_rcp_f32_e32 v3, v3
	v_mov_b32_e32 v1, v2
	v_pk_mul_f32 v[146:147], v[0:1], v[144:145]
	v_mul_f32_e32 v2, v227, v3
	v_exp_f32_e32 v148, v2
	v_fma_f32 v2, v8, s59, v243
	v_exp_f32_e32 v2, v2
	v_fma_f32 v3, -v148, v148, 1.0
	v_add_f32_e32 v2, 1.0, v2
	v_rcp_f32_e32 v2, v2
	v_pk_fma_f32 v[0:1], v[0:1], v[144:145], v[146:147] op_sel:[0,0,1] op_sel_hi:[1,1,0]
	v_mul_f32_e32 v5, v5, v148
	s_nop 0
	s_nop 1
	s_nop 1
	v_sqrt_f32_e32 v3, v3
	s_nop 0
	v_mul_f32_e32 v2, v2, v3
	v_fma_f32 v3, v25, s59, v242
	v_exp_f32_e32 v3, v3
	v_mov_b32_e32 v1, v2
	ds_read_u16 v4, v228 offset:35968
	ds_read_u16 v6, v228 offset:36240
	ds_read_u16 v7, v228 offset:36512
	ds_read_u16 v8, v228 offset:36784
	ds_read_u16 v16, v228 offset:37056
	ds_read_u16 v17, v228 offset:37328
	ds_read_u16 v18, v228 offset:37600
	ds_read_u16 v19, v228 offset:37872
	s_waitcnt lgkmcnt(7)
	v_lshlrev_b32_e32 v149, 16, v4
	v_add_f32_e32 v3, 1.0, v3
	v_rcp_f32_e32 v3, v3
	v_pk_mul_f32 v[150:151], v[0:1], v[148:149]
	s_waitcnt lgkmcnt(6)
	v_lshlrev_b32_e32 v153, 16, v6
	v_pk_fma_f32 v[0:1], v[0:1], v[148:149], v[150:151] op_sel:[0,0,1] op_sel_hi:[1,1,0]
	v_mul_f32_e32 v2, v227, v3
	v_exp_f32_e32 v152, v2
	v_fma_f32 v2, v9, s59, v243
	v_exp_f32_e32 v2, v2
	v_fma_f32 v3, -v152, v152, 1.0
	v_add_f32_e32 v2, 1.0, v2
	v_rcp_f32_e32 v2, v2
	s_waitcnt lgkmcnt(5)
	v_lshlrev_b32_e32 v157, 16, v7
	s_waitcnt lgkmcnt(4)
	v_lshlrev_b32_e32 v161, 16, v8
	s_waitcnt lgkmcnt(3)
	v_lshlrev_b32_e32 v165, 16, v16
	s_waitcnt lgkmcnt(2)
	v_lshlrev_b32_e32 v169, 16, v17
	v_mul_f32_e32 v5, v5, v152
	s_waitcnt lgkmcnt(1)
	v_lshlrev_b32_e32 v173, 16, v18
	v_fma_f32 v9, v26, s59, v242
	v_exp_f32_e32 v9, v9
	s_waitcnt lgkmcnt(0)
	v_lshlrev_b32_e32 v177, 16, v19
	v_mov_b32_e32 v150, v107
	v_sqrt_f32_e32 v3, v3
	s_nop 0
	v_mul_f32_e32 v2, v2, v3
	v_add_f32_e32 v3, 1.0, v9
	v_rcp_f32_e32 v3, v3
	v_mov_b32_e32 v1, v2
	v_pk_mul_f32 v[154:155], v[0:1], v[152:153]
	v_mul_f32_e32 v2, v227, v3
	v_exp_f32_e32 v156, v2
	v_fma_f32 v2, v10, s59, v243
	v_exp_f32_e32 v2, v2
	v_fma_f32 v3, -v156, v156, 1.0
	v_add_f32_e32 v2, 1.0, v2
	v_rcp_f32_e32 v2, v2
	v_pk_fma_f32 v[0:1], v[0:1], v[152:153], v[154:155] op_sel:[0,0,1] op_sel_hi:[1,1,0]
	v_mul_f32_e32 v5, v5, v156
	v_mov_b32_e32 v153, 0
	s_nop 0
	s_nop 1
	v_fma_f32 v6, v27, s59, v242
	v_exp_f32_e32 v6, v6
	s_nop 1
	v_sqrt_f32_e32 v3, v3
	s_nop 0
	v_mul_f32_e32 v2, v2, v3
	v_add_f32_e32 v3, 1.0, v6
	v_rcp_f32_e32 v3, v3
	v_mov_b32_e32 v1, v2
	v_pk_mul_f32 v[158:159], v[0:1], v[156:157]
	v_mul_f32_e32 v2, v227, v3
	v_exp_f32_e32 v160, v2
	v_fma_f32 v2, v11, s59, v243
	v_exp_f32_e32 v2, v2
	v_fma_f32 v3, -v160, v160, 1.0
	v_add_f32_e32 v2, 1.0, v2
	v_rcp_f32_e32 v2, v2
	v_pk_fma_f32 v[0:1], v[0:1], v[156:157], v[158:159] op_sel:[0,0,1] op_sel_hi:[1,1,0]
	v_mul_f32_e32 v5, v5, v160
	s_nop 0
	s_nop 1
	v_fma_f32 v6, v28, s59, v242
	v_exp_f32_e32 v6, v6
	s_nop 1
	v_sqrt_f32_e32 v3, v3
	s_nop 0
	v_mul_f32_e32 v2, v2, v3
	v_add_f32_e32 v3, 1.0, v6
	v_rcp_f32_e32 v3, v3
	v_mov_b32_e32 v1, v2
	v_pk_mul_f32 v[162:163], v[0:1], v[160:161]
	v_mul_f32_e32 v2, v227, v3
	v_exp_f32_e32 v164, v2
	v_fma_f32 v2, v12, s59, v243
	v_exp_f32_e32 v2, v2
	v_fma_f32 v3, -v164, v164, 1.0
	v_add_f32_e32 v2, 1.0, v2
	v_rcp_f32_e32 v2, v2
	v_pk_fma_f32 v[0:1], v[0:1], v[160:161], v[162:163] op_sel:[0,0,1] op_sel_hi:[1,1,0]
	v_mul_f32_e32 v5, v5, v164
	s_nop 0
	s_nop 1
	v_fma_f32 v6, v29, s59, v242
	v_exp_f32_e32 v6, v6
	s_nop 1
	v_sqrt_f32_e32 v3, v3
	s_nop 0
	v_mul_f32_e32 v2, v2, v3
	v_add_f32_e32 v3, 1.0, v6
	v_rcp_f32_e32 v3, v3
	v_mov_b32_e32 v1, v2
	v_pk_mul_f32 v[166:167], v[0:1], v[164:165]
	v_mul_f32_e32 v2, v227, v3
	v_exp_f32_e32 v168, v2
	v_fma_f32 v2, v13, s59, v243
	v_exp_f32_e32 v2, v2
	v_fma_f32 v3, -v168, v168, 1.0
	v_add_f32_e32 v2, 1.0, v2
	v_rcp_f32_e32 v2, v2
	v_pk_fma_f32 v[0:1], v[0:1], v[164:165], v[166:167] op_sel:[0,0,1] op_sel_hi:[1,1,0]
	v_mul_f32_e32 v5, v5, v168
	s_nop 0
	s_nop 1
	v_fma_f32 v6, v30, s59, v242
	v_exp_f32_e32 v6, v6
	s_nop 1
	v_sqrt_f32_e32 v3, v3
	s_nop 0
	v_mul_f32_e32 v2, v2, v3
	v_add_f32_e32 v3, 1.0, v6
	v_rcp_f32_e32 v3, v3
	v_mov_b32_e32 v1, v2
	v_pk_mul_f32 v[170:171], v[0:1], v[168:169]
	v_mul_f32_e32 v2, v227, v3
	v_exp_f32_e32 v172, v2
	v_fma_f32 v2, v14, s59, v243
	v_exp_f32_e32 v2, v2
	v_fma_f32 v3, -v172, v172, 1.0
	v_add_f32_e32 v2, 1.0, v2
	v_rcp_f32_e32 v2, v2
	v_pk_fma_f32 v[0:1], v[0:1], v[168:169], v[170:171] op_sel:[0,0,1] op_sel_hi:[1,1,0]
	v_mul_f32_e32 v5, v5, v172
	s_nop 0
	s_nop 1
	v_fma_f32 v6, v31, s59, v242
	v_exp_f32_e32 v6, v6
	s_nop 1
	v_sqrt_f32_e32 v3, v3
	s_nop 0
	v_mul_f32_e32 v2, v2, v3
	v_add_f32_e32 v3, 1.0, v6
	v_rcp_f32_e32 v3, v3
	v_mov_b32_e32 v1, v2
	v_pk_mul_f32 v[174:175], v[0:1], v[172:173]
	v_mul_f32_e32 v2, v227, v3
	v_exp_f32_e32 v176, v2
	v_fma_f32 v2, v15, s59, v243
	v_exp_f32_e32 v2, v2
	v_fma_f32 v3, -v176, v176, 1.0
	v_add_f32_e32 v2, 1.0, v2
	v_rcp_f32_e32 v2, v2
	v_pk_fma_f32 v[0:1], v[0:1], v[172:173], v[174:175] op_sel:[0,0,1] op_sel_hi:[1,1,0]
	s_nop 0
	s_nop 1
	s_add_i32 s8, s30, s10
	v_add3_u32 v117, s8, v215, v216
	v_sqrt_f32_e32 v3, v3
	s_nop 0
	v_mul_f32_e32 v2, v2, v3
	v_mov_b32_e32 v1, v2
	v_pk_mul_f32 v[178:179], v[0:1], v[176:177]
	s_mul_i32 s10, s23, 0x60000
	v_pk_fma_f32 v[0:1], v[0:1], v[176:177], v[178:179] op_sel_hi:[1,1,0]
	s_nop 0
	v_mul_f32_e32 v0, v5, v176
	ds_write_b64 v117, v[0:1] offset:17408
	v_add_co_u32_e32 v0, vcc, s60, v84
	s_waitcnt lgkmcnt(0)
	s_waitcnt vmcnt(15)
	ds_write_b128 v222, v[52:55] offset:33792
	s_waitcnt vmcnt(14)
	ds_write_b128 v222, v[60:63] offset:34880
	s_waitcnt vmcnt(13)
	ds_write_b128 v222, v[68:71] offset:35968
	s_waitcnt vmcnt(12)
	ds_write_b128 v222, v[76:79] offset:37056
	s_waitcnt vmcnt(11)
	ds_write_b128 v222, v[80:83] offset:38144
	s_waitcnt vmcnt(10)
	ds_write_b128 v222, v[88:91] offset:39232
	s_waitcnt vmcnt(9)
	ds_write_b128 v222, v[92:95] offset:40320
	s_waitcnt vmcnt(8)
	ds_write_b128 v222, v[96:99] offset:41408
	v_addc_co_u32_e32 v1, vcc, 0, v85, vcc
	v_add_co_u32_e32 v2, vcc, s61, v84
	s_nop 1
	v_addc_co_u32_e32 v3, vcc, 0, v85, vcc
	global_load_dwordx4 v[52:55], v[0:1], off
	global_load_dwordx4 v[60:63], v[2:3], off offset:2048
	v_add_co_u32_e32 v0, vcc, s62, v84
	s_nop 1
	v_addc_co_u32_e32 v1, vcc, 0, v85, vcc
	v_add_co_u32_e32 v2, vcc, s63, v84
	s_nop 1
	v_addc_co_u32_e32 v3, vcc, 0, v85, vcc
	global_load_dwordx4 v[68:71], v[0:1], off
	global_load_dwordx4 v[76:79], v[2:3], off offset:2048
	v_add_co_u32_e32 v0, vcc, s64, v84
	s_nop 1
	v_addc_co_u32_e32 v1, vcc, 0, v85, vcc
	v_add_co_u32_e32 v2, vcc, s65, v84
	s_nop 1
	v_addc_co_u32_e32 v3, vcc, 0, v85, vcc
	global_load_dwordx4 v[80:83], v[0:1], off
	global_load_dwordx4 v[88:91], v[2:3], off offset:2048
	v_add_co_u32_e32 v0, vcc, s66, v84
	s_nop 1
	v_addc_co_u32_e32 v1, vcc, 0, v85, vcc
	v_add_co_u32_e32 v2, vcc, s67, v84
	s_nop 1
	v_addc_co_u32_e32 v3, vcc, 0, v85, vcc
	global_load_dwordx4 v[92:95], v[0:1], off
	global_load_dwordx4 v[96:99], v[2:3], off offset:2048
	s_waitcnt lgkmcnt(0)
	ds_read_b128 v[0:3], v223 offset:33792
	ds_read_b128 v[4:7], v86
	ds_read_b128 v[180:183], v223 offset:33824
	ds_read_b128 v[184:187], v86 offset:32
	s_waitcnt lgkmcnt(2)
	v_mfma_f32_32x32x16_bf16 v[16:31], v[0:3], v[4:7], 0
	ds_read_b128 v[4:7], v86 offset:8704
	ds_read_b128 v[188:191], v86 offset:8736
	s_waitcnt lgkmcnt(1)
	v_mfma_f32_32x32x16_bf16 v[0:15], v[0:3], v[4:7], 0
	v_mfma_f32_32x32x16_bf16 v[16:31], v[180:183], v[184:187], v[16:31]
	s_waitcnt lgkmcnt(0)
	v_mfma_f32_32x32x16_bf16 v[0:15], v[180:183], v[188:191], v[0:15]
	ds_read_b128 v[180:183], v223 offset:33856
	ds_read_b128 v[184:187], v86 offset:64
	ds_read_b128 v[188:191], v223 offset:33888
	ds_read_b128 v[192:195], v86 offset:96
	s_waitcnt lgkmcnt(2)
	v_mfma_f32_32x32x16_bf16 v[16:31], v[180:183], v[184:187], v[16:31]
	ds_read_b128 v[184:187], v86 offset:8768
	ds_read_b128 v[196:199], v86 offset:8800
	s_waitcnt lgkmcnt(1)
	v_mfma_f32_32x32x16_bf16 v[0:15], v[180:183], v[184:187], v[0:15]
	v_mfma_f32_32x32x16_bf16 v[16:31], v[188:191], v[192:195], v[16:31]
	s_waitcnt lgkmcnt(0)
	v_mfma_f32_32x32x16_bf16 v[0:15], v[188:191], v[196:199], v[0:15]
	ds_read_b128 v[180:183], v223 offset:33920
	ds_read_b128 v[184:187], v86 offset:128
	ds_read_b128 v[188:191], v223 offset:33952
	ds_read_b128 v[192:195], v86 offset:160
	s_waitcnt lgkmcnt(2)
	v_mfma_f32_32x32x16_bf16 v[16:31], v[180:183], v[184:187], v[16:31]
	ds_read_b128 v[184:187], v86 offset:8832
	ds_read_b128 v[196:199], v86 offset:8864
	s_waitcnt lgkmcnt(1)
	v_mfma_f32_32x32x16_bf16 v[0:15], v[180:183], v[184:187], v[0:15]
	v_mfma_f32_32x32x16_bf16 v[16:31], v[188:191], v[192:195], v[16:31]
	s_waitcnt lgkmcnt(0)
	v_mfma_f32_32x32x16_bf16 v[0:15], v[188:191], v[196:199], v[0:15]
	ds_read_b128 v[180:183], v223 offset:33984
	ds_read_b128 v[184:187], v86 offset:192
	ds_read_b128 v[188:191], v223 offset:34016
	ds_read_b128 v[192:195], v86 offset:224
	s_waitcnt lgkmcnt(2)
	v_mfma_f32_32x32x16_bf16 v[16:31], v[180:183], v[184:187], v[16:31]
	ds_read_b128 v[184:187], v86 offset:8896
	ds_read_b128 v[196:199], v86 offset:8928
	s_waitcnt lgkmcnt(2)
	v_mfma_f32_32x32x16_bf16 v[16:31], v[188:191], v[192:195], v[16:31]
	s_waitcnt lgkmcnt(1)
	v_mfma_f32_32x32x16_bf16 v[0:15], v[180:183], v[184:187], v[0:15]
	s_nop 9
	v_fma_f32 v16, v16, s59, v242
	v_exp_f32_e32 v16, v16
	v_fma_f32 v17, v17, s59, v242
	v_fma_f32 v18, v18, s59, v242
	v_add_f32_e32 v16, 1.0, v16
	v_rcp_f32_e32 v16, v16
	s_waitcnt lgkmcnt(0)
	v_mfma_f32_32x32x16_bf16 v[0:15], v[188:191], v[196:199], v[0:15]
	v_exp_f32_e32 v18, v18
	v_mul_f32_e32 v16, v227, v16
	v_exp_f32_e32 v16, v16
	v_fma_f32 v19, v19, s59, v242
	v_add_f32_e32 v18, 1.0, v18
	v_rcp_f32_e32 v18, v18
	v_fma_f32 v84, -v16, v16, 1.0
	s_nop 1
	s_nop 1
	s_nop 0
	v_fma_f32 v0, v0, s59, v243
	v_exp_f32_e32 v0, v0
	v_fma_f32 v1, v1, s59, v243
	v_add_f32_e32 v0, 1.0, v0
	v_rcp_f32_e32 v0, v0
	v_exp_f32_e32 v1, v1
	v_exp_f32_e32 v86, v17
	v_add_f32_e32 v1, 1.0, v1
	v_rcp_f32_e32 v1, v1
	v_sqrt_f32_e32 v17, v84
	s_nop 0
	v_mul_f32_e32 v17, v0, v17
	v_add_f32_e32 v0, 1.0, v86
	v_rcp_f32_e32 v0, v0
	ds_read_u16 v84, v228 offset:33792
	ds_read_u16 v85, v228 offset:34064
	ds_read_u16 v86, v228 offset:34336
	ds_read_u16 v119, v228 offset:34608
	ds_read_u16 v120, v228 offset:34880
	ds_read_u16 v122, v228 offset:35152
	ds_read_u16 v125, v228 offset:35424
	ds_read_u16 v126, v228 offset:35696
	s_waitcnt lgkmcnt(7)
	v_lshlrev_b32_e32 v103, 16, v84
	v_pk_mul_f32 v[180:181], v[16:17], v[102:103]
	v_mul_f32_e32 v0, v227, v0
	v_exp_f32_e32 v0, v0
	v_fma_f32 v2, v2, s59, v243
	v_exp_f32_e32 v2, v2
	v_fma_f32 v84, -v0, v0, 1.0
	v_add_f32_e32 v2, 1.0, v2
	v_rcp_f32_e32 v2, v2
	v_fma_f32 v20, v20, s59, v242
	v_exp_f32_e32 v20, v20
	v_fma_f32 v21, v21, s59, v242
	s_nop 1
	v_sqrt_f32_e32 v84, v84
	s_nop 0
	v_mul_f32_e32 v129, v1, v84
	s_waitcnt lgkmcnt(6)
	v_lshlrev_b32_e32 v1, 16, v85
	v_pk_fma_f32 v[84:85], v[16:17], v[102:103], v[180:181] op_sel:[0,0,1] op_sel_hi:[1,1,0]
	v_mul_f32_e32 v17, v227, v18
	v_exp_f32_e32 v18, v17
	v_mov_b32_e32 v85, v129
	v_pk_mul_f32 v[182:183], v[84:85], v[0:1]
	v_mul_f32_e32 v129, v16, v0
	v_fma_f32 v17, -v18, v18, 1.0
	v_pk_fma_f32 v[84:85], v[84:85], v[0:1], v[182:183] op_sel:[0,0,1] op_sel_hi:[1,1,0]
	s_nop 0
	s_nop 0
	s_nop 0
	s_nop 1
	v_exp_f32_e32 v130, v19
	s_waitcnt lgkmcnt(5)
	v_lshlrev_b32_e32 v19, 16, v86
	v_mul_f32_e32 v86, v129, v18
	v_sqrt_f32_e32 v17, v17
	s_nop 0
	v_mul_f32_e32 v2, v2, v17
	v_add_f32_e32 v17, 1.0, v130
	v_rcp_f32_e32 v17, v17
	v_mov_b32_e32 v85, v2
	v_pk_mul_f32 v[184:185], v[84:85], v[18:19]
	v_mul_f32_e32 v1, v227, v17
	v_exp_f32_e32 v2, v1
	v_fma_f32 v1, v3, s59, v243
	v_exp_f32_e32 v1, v1
	v_fma_f32 v3, -v2, v2, 1.0
	v_add_f32_e32 v1, 1.0, v1
	v_rcp_f32_e32 v1, v1
	v_pk_fma_f32 v[84:85], v[84:85], v[18:19], v[184:185] op_sel:[0,0,1] op_sel_hi:[1,1,0]
	v_mul_f32_e32 v19, v86, v2
	s_nop 0
	s_nop 1
	s_nop 1
	v_sqrt_f32_e32 v3, v3
	s_nop 0
	v_add_f32_e32 v17, 1.0, v20
	v_rcp_f32_e32 v17, v17
	v_mul_f32_e32 v1, v1, v3
	v_mov_b32_e32 v85, v1
	s_waitcnt lgkmcnt(4)
	v_lshlrev_b32_e32 v3, 16, v119
	v_mul_f32_e32 v1, v227, v17
	v_exp_f32_e32 v20, v1
	v_fma_f32 v1, v4, s59, v243
	v_exp_f32_e32 v1, v1
	v_fma_f32 v4, -v20, v20, 1.0
	v_add_f32_e32 v1, 1.0, v1
	v_rcp_f32_e32 v1, v1
	v_pk_mul_f32 v[186:187], v[84:85], v[2:3]
	v_pk_fma_f32 v[84:85], v[84:85], v[2:3], v[186:187] op_sel:[0,0,1] op_sel_hi:[1,1,0]
	s_nop 1
	v_exp_f32_e32 v86, v21
	s_waitcnt lgkmcnt(3)
	v_lshlrev_b32_e32 v21, 16, v120
	v_sqrt_f32_e32 v4, v4
	s_nop 0
	v_mul_f32_e32 v1, v1, v4
	v_add_f32_e32 v4, 1.0, v86
	v_rcp_f32_e32 v4, v4
	v_mov_b32_e32 v85, v1
	v_mul_f32_e32 v17, v19, v20
	v_pk_mul_f32 v[188:189], v[84:85], v[20:21]
	v_mul_f32_e32 v1, v227, v4
	v_exp_f32_e32 v4, v1
	v_fma_f32 v1, v5, s59, v243
	v_exp_f32_e32 v1, v1
	v_fma_f32 v3, -v4, v4, 1.0
	v_add_f32_e32 v1, 1.0, v1
	v_rcp_f32_e32 v1, v1
	v_pk_fma_f32 v[84:85], v[84:85], v[20:21], v[188:189] op_sel:[0,0,1] op_sel_hi:[1,1,0]
	v_mul_f32_e32 v17, v17, v4
	s_nop 0
	s_nop 1
	v_fma_f32 v19, v22, s59, v242
	v_exp_f32_e32 v19, v19
	s_nop 1
	v_sqrt_f32_e32 v3, v3
	s_nop 0
	v_mul_f32_e32 v1, v1, v3
	v_add_f32_e32 v3, 1.0, v19
	v_rcp_f32_e32 v3, v3
	v_mov_b32_e32 v85, v1
	s_waitcnt lgkmcnt(2)
	v_lshlrev_b32_e32 v5, 16, v122
	v_pk_mul_f32 v[190:191], v[84:85], v[4:5]
	v_mul_f32_e32 v1, v227, v3
	v_exp_f32_e32 v22, v1
	v_fma_f32 v1, v6, s59, v243
	v_exp_f32_e32 v1, v1
	v_fma_f32 v3, -v22, v22, 1.0
	v_add_f32_e32 v1, 1.0, v1
	v_rcp_f32_e32 v1, v1
	v_pk_fma_f32 v[84:85], v[84:85], v[4:5], v[190:191] op_sel:[0,0,1] op_sel_hi:[1,1,0]
	v_mul_f32_e32 v17, v17, v22
	s_nop 0
	s_nop 1
	v_fma_f32 v19, v23, s59, v242
	v_exp_f32_e32 v19, v19
	s_waitcnt lgkmcnt(1)
	v_lshlrev_b32_e32 v23, 16, v125
	v_sqrt_f32_e32 v3, v3
	s_nop 0
	v_mul_f32_e32 v1, v1, v3
	v_add_f32_e32 v3, 1.0, v19
	v_rcp_f32_e32 v3, v3
	v_mov_b32_e32 v85, v1
	v_pk_mul_f32 v[192:193], v[84:85], v[22:23]
	v_mul_f32_e32 v1, v227, v3
	v_exp_f32_e32 v6, v1
	v_fma_f32 v1, v7, s59, v243
	v_exp_f32_e32 v1, v1
	v_fma_f32 v3, -v6, v6, 1.0
	v_add_f32_e32 v1, 1.0, v1
	v_rcp_f32_e32 v1, v1
	v_pk_fma_f32 v[84:85], v[84:85], v[22:23], v[192:193] op_sel:[0,0,1] op_sel_hi:[1,1,0]
	v_mul_f32_e32 v17, v17, v6
	s_nop 0
	s_nop 1
	v_fma_f32 v7, v24, s59, v242
	v_exp_f32_e32 v19, v7
	s_waitcnt lgkmcnt(0)
	v_lshlrev_b32_e32 v7, 16, v126
	v_sqrt_f32_e32 v3, v3
	s_nop 0
	v_mul_f32_e32 v1, v1, v3
	v_add_f32_e32 v3, 1.0, v19
	v_rcp_f32_e32 v3, v3
	v_mov_b32_e32 v85, v1
	v_pk_mul_f32 v[194:195], v[84:85], v[6:7]
	v_mul_f32_e32 v1, v227, v3
	v_exp_f32_e32 v24, v1
	v_fma_f32 v1, v8, s59, v243
	v_exp_f32_e32 v1, v1
	v_fma_f32 v3, -v24, v24, 1.0
	v_add_f32_e32 v1, 1.0, v1
	v_rcp_f32_e32 v1, v1
	v_pk_fma_f32 v[84:85], v[84:85], v[6:7], v[194:195] op_sel:[0,0,1] op_sel_hi:[1,1,0]
	v_mul_f32_e32 v7, v17, v24
	s_nop 0
	s_nop 1
	s_nop 1
	v_sqrt_f32_e32 v3, v3
	s_nop 0
	v_mul_f32_e32 v1, v1, v3
	v_fma_f32 v3, v25, s59, v242
	v_exp_f32_e32 v3, v3
	v_mov_b32_e32 v85, v1
	ds_read_u16 v5, v228 offset:35968
	ds_read_u16 v19, v228 offset:36240
	ds_read_u16 v21, v228 offset:36512
	ds_read_u16 v23, v228 offset:36784
	ds_read_u16 v86, v228 offset:37056
	ds_read_u16 v103, v228 offset:37328
	ds_read_u16 v119, v228 offset:37600
	ds_read_u16 v120, v228 offset:37872
	s_waitcnt lgkmcnt(7)
	v_lshlrev_b32_e32 v25, 16, v5
	v_add_f32_e32 v3, 1.0, v3
	v_rcp_f32_e32 v3, v3
	v_pk_mul_f32 v[196:197], v[84:85], v[24:25]
	v_mul_f32_e32 v1, v227, v3
	v_exp_f32_e32 v8, v1
	v_fma_f32 v1, v9, s59, v243
	v_exp_f32_e32 v1, v1
	v_fma_f32 v3, -v8, v8, 1.0
	v_add_f32_e32 v1, 1.0, v1
	v_rcp_f32_e32 v1, v1
	v_pk_fma_f32 v[84:85], v[84:85], v[24:25], v[196:197] op_sel:[0,0,1] op_sel_hi:[1,1,0]
	v_mul_f32_e32 v7, v7, v8
	s_nop 0
	s_nop 1
	v_fma_f32 v9, v26, s59, v242
	v_exp_f32_e32 v17, v9
	s_waitcnt lgkmcnt(6)
	v_lshlrev_b32_e32 v9, 16, v19
	v_sqrt_f32_e32 v3, v3
	s_nop 0
	v_mul_f32_e32 v1, v1, v3
	v_add_f32_e32 v3, 1.0, v17
	v_rcp_f32_e32 v3, v3
	v_mov_b32_e32 v85, v1
	v_pk_mul_f32 v[198:199], v[84:85], v[8:9]
	v_mul_f32_e32 v1, v227, v3
	v_exp_f32_e32 v26, v1
	v_fma_f32 v1, v10, s59, v243
	v_exp_f32_e32 v1, v1
	v_fma_f32 v3, -v26, v26, 1.0
	v_add_f32_e32 v1, 1.0, v1
	v_rcp_f32_e32 v1, v1
	v_pk_fma_f32 v[84:85], v[84:85], v[8:9], v[198:199] op_sel:[0,0,1] op_sel_hi:[1,1,0]
	v_mul_f32_e32 v7, v7, v26
	s_nop 0
	s_nop 1
	v_fma_f32 v10, v27, s59, v242
	v_exp_f32_e32 v10, v10
	s_waitcnt lgkmcnt(5)
	v_lshlrev_b32_e32 v27, 16, v21
	v_sqrt_f32_e32 v3, v3
	s_nop 0
	v_mul_f32_e32 v1, v1, v3
	v_add_f32_e32 v3, 1.0, v10
	v_rcp_f32_e32 v3, v3
	v_mov_b32_e32 v85, v1
	v_pk_mul_f32 v[200:201], v[84:85], v[26:27]
	v_mul_f32_e32 v1, v227, v3
	v_exp_f32_e32 v10, v1
	v_fma_f32 v1, v11, s59, v243
	v_exp_f32_e32 v1, v1
	v_fma_f32 v3, -v10, v10, 1.0
	v_add_f32_e32 v1, 1.0, v1
	v_rcp_f32_e32 v1, v1
	v_pk_fma_f32 v[84:85], v[84:85], v[26:27], v[200:201] op_sel:[0,0,1] op_sel_hi:[1,1,0]
	v_mul_f32_e32 v7, v7, v10
	s_nop 0
	s_nop 1
	v_fma_f32 v9, v28, s59, v242
	v_exp_f32_e32 v9, v9
	s_waitcnt lgkmcnt(4)
	v_lshlrev_b32_e32 v11, 16, v23
	v_sqrt_f32_e32 v3, v3
	s_nop 0
	v_mul_f32_e32 v1, v1, v3
	v_add_f32_e32 v3, 1.0, v9
	v_rcp_f32_e32 v3, v3
	v_mov_b32_e32 v85, v1
	v_pk_mul_f32 v[202:203], v[84:85], v[10:11]
	v_mul_f32_e32 v1, v227, v3
	v_exp_f32_e32 v28, v1
	v_fma_f32 v1, v12, s59, v243
	v_exp_f32_e32 v1, v1
	v_fma_f32 v3, -v28, v28, 1.0
	v_add_f32_e32 v1, 1.0, v1
	v_rcp_f32_e32 v1, v1
	v_pk_fma_f32 v[84:85], v[84:85], v[10:11], v[202:203] op_sel:[0,0,1] op_sel_hi:[1,1,0]
	v_mul_f32_e32 v7, v7, v28
	s_nop 0
	s_nop 1
	v_fma_f32 v9, v29, s59, v242
	v_exp_f32_e32 v9, v9
	s_waitcnt lgkmcnt(3)
	v_lshlrev_b32_e32 v29, 16, v86
	v_sqrt_f32_e32 v3, v3
	s_nop 0
	v_mul_f32_e32 v1, v1, v3
	v_add_f32_e32 v3, 1.0, v9
	v_rcp_f32_e32 v3, v3
	v_mov_b32_e32 v85, v1
	v_pk_mul_f32 v[204:205], v[84:85], v[28:29]
	v_mul_f32_e32 v1, v227, v3
	v_exp_f32_e32 v12, v1
	v_fma_f32 v1, v13, s59, v243
	v_exp_f32_e32 v1, v1
	v_fma_f32 v3, -v12, v12, 1.0
	v_add_f32_e32 v1, 1.0, v1
	v_rcp_f32_e32 v1, v1
	v_pk_fma_f32 v[84:85], v[84:85], v[28:29], v[204:205] op_sel:[0,0,1] op_sel_hi:[1,1,0]
	s_waitcnt lgkmcnt(2)
	v_lshlrev_b32_e32 v13, 16, v103
	v_mul_f32_e32 v7, v7, v12
	s_nop 0
	s_nop 1
	v_fma_f32 v9, v30, s59, v242
	v_exp_f32_e32 v9, v9
	s_nop 1
	v_sqrt_f32_e32 v3, v3
	s_nop 0
	v_mul_f32_e32 v1, v1, v3
	v_add_f32_e32 v3, 1.0, v9
	v_rcp_f32_e32 v3, v3
	v_mov_b32_e32 v85, v1
	v_pk_mul_f32 v[206:207], v[84:85], v[12:13]
	v_mul_f32_e32 v1, v227, v3
	v_exp_f32_e32 v30, v1
	v_fma_f32 v1, v14, s59, v243
	v_exp_f32_e32 v1, v1
	v_fma_f32 v3, -v30, v30, 1.0
	v_add_f32_e32 v1, 1.0, v1
	v_rcp_f32_e32 v1, v1
	v_pk_fma_f32 v[84:85], v[84:85], v[12:13], v[206:207] op_sel:[0,0,1] op_sel_hi:[1,1,0]
	v_mul_f32_e32 v7, v7, v30
	s_nop 0
	s_nop 1
	v_fma_f32 v9, v31, s59, v242
	v_exp_f32_e32 v9, v9
	s_waitcnt lgkmcnt(1)
	v_lshlrev_b32_e32 v31, 16, v119
	v_sqrt_f32_e32 v3, v3
	s_nop 0
	v_mul_f32_e32 v1, v1, v3
	v_add_f32_e32 v3, 1.0, v9
	v_rcp_f32_e32 v3, v3
	v_mov_b32_e32 v85, v1
	v_pk_mul_f32 v[208:209], v[84:85], v[30:31]
	v_mul_f32_e32 v1, v227, v3
	v_exp_f32_e32 v14, v1
	v_fma_f32 v1, v15, s59, v243
	v_exp_f32_e32 v1, v1
	v_fma_f32 v3, -v14, v14, 1.0
	v_add_f32_e32 v1, 1.0, v1
	v_rcp_f32_e32 v1, v1
	v_pk_fma_f32 v[84:85], v[84:85], v[30:31], v[208:209] op_sel:[0,0,1] op_sel_hi:[1,1,0]
	s_waitcnt lgkmcnt(0)
	v_lshlrev_b32_e32 v15, 16, v120
	s_nop 0
	s_nop 1
	s_ashr_i32 s9, s10, 31
	s_mov_b32 s8, s10
	v_sqrt_f32_e32 v3, v3
	s_nop 0
	v_mul_f32_e32 v1, v1, v3
	v_mov_b32_e32 v85, v1
	v_lshl_add_u64 v[230:231], s[8:9], 1, v[112:113]
	v_pk_mul_f32 v[210:211], v[84:85], v[14:15]
	v_add_co_u32_e32 v232, vcc, s52, v230
	v_pk_fma_f32 v[84:85], v[84:85], v[14:15], v[210:211] op_sel_hi:[1,1,0]
	s_nop 0
	v_addc_co_u32_e32 v233, vcc, 0, v231, vcc
	v_mul_f32_e32 v84, v7, v14
	v_add_co_u32_e32 v234, vcc, s51, v230
	ds_write_b64 v117, v[84:85] offset:17920
	v_lshl_add_u64 v[84:85], s[10:11], 1, v[112:113]
	v_addc_co_u32_e32 v235, vcc, 0, v231, vcc
	s_waitcnt lgkmcnt(0)
	s_waitcnt lgkmcnt(0)
	s_barrier
	global_load_ushort v146, v[84:85], off
	global_load_ushort v145, v[230:231], off offset:1536
	global_load_ushort v141, v[230:231], off offset:3072
	global_load_ushort v138, v[232:233], off offset:512
	global_load_ushort v137, v[232:233], off offset:2048
	global_load_ushort v134, v[232:233], off offset:3584
	global_load_ushort v133, v[234:235], off offset:1024
	global_load_ushort v125, v[234:235], off offset:2560
	v_add_co_u32_e32 v84, vcc, s53, v230
	s_mov_b32 s10, 0
	s_nop 0
	v_addc_co_u32_e32 v85, vcc, 0, v231, vcc
	v_add_co_u32_e32 v232, vcc, s54, v230
	s_nop 1
	v_addc_co_u32_e32 v233, vcc, 0, v231, vcc
	v_add_co_u32_e32 v234, vcc, s68, v230
	s_nop 1
	v_addc_co_u32_e32 v235, vcc, 0, v231, vcc
	global_load_ushort v130, v[84:85], off
	global_load_ushort v129, v[84:85], off offset:1536
	global_load_ushort v126, v[84:85], off offset:3072
	global_load_ushort v122, v[232:233], off offset:512
	global_load_ushort v120, v[232:233], off offset:2048
	global_load_ushort v117, v[232:233], off offset:3584
	global_load_ushort v103, v[234:235], off offset:1024
	global_load_ushort v29, v[234:235], off offset:2560
	v_add_co_u32_e32 v84, vcc, s60, v230
	s_nop 1
	v_addc_co_u32_e32 v85, vcc, 0, v231, vcc
	v_add_co_u32_e32 v232, vcc, s61, v230
	s_nop 1
	v_addc_co_u32_e32 v233, vcc, 0, v231, vcc
	v_add_co_u32_e32 v234, vcc, 0xe000, v230
	s_nop 1
	v_addc_co_u32_e32 v235, vcc, 0, v231, vcc
	global_load_ushort v119, v[84:85], off
	global_load_ushort v31, v[84:85], off offset:1536
	global_load_ushort v27, v[84:85], off offset:3072
	global_load_ushort v25, v[232:233], off offset:512
	global_load_ushort v23, v[232:233], off offset:2048
	global_load_ushort v19, v[232:233], off offset:3584
	global_load_ushort v17, v[234:235], off offset:1024
	global_load_ushort v13, v[234:235], off offset:2560
	v_add_co_u32_e32 v84, vcc, s62, v230
	s_nop 1
	v_addc_co_u32_e32 v85, vcc, 0, v231, vcc
	v_add_co_u32_e32 v232, vcc, 0x10000, v230
	s_nop 1
	v_addc_co_u32_e32 v233, vcc, 0, v231, vcc
	v_add_co_u32_e32 v230, vcc, 0x11000, v230
	s_nop 1
	v_addc_co_u32_e32 v231, vcc, 0, v231, vcc
	global_load_ushort v21, v[84:85], off
	global_load_ushort v15, v[84:85], off offset:1536
	global_load_ushort v11, v[84:85], off offset:3072
	global_load_ushort v9, v[232:233], off offset:512
	global_load_ushort v7, v[232:233], off offset:2048
	global_load_ushort v5, v[232:233], off offset:3584
	global_load_ushort v3, v[230:231], off offset:1024
	global_load_ushort v1, v[230:231], off offset:2560
	v_cndmask_b32_e64 v84, 0, 1, s[20:21]
	v_lshl_add_u32 v149, v84, 13, v218

.LBB0_1086:
	s_or_b64 exec, exec, s[96:97]
	v_cndmask_b32_e64 v1, 0, 1, vcc
	v_or_b32_e32 v4, s79, v1
	v_lshlrev_b32_e32 v1, 7, v4
	v_and_b32_e32 v131, 0x60, v2
	v_or3_b32 v2, v1, v131, s90
	v_mov_b32_e32 v3, s91
	v_cndmask_b32_e32 v1, 0, v124, vcc
	v_lshlrev_b64 v[2:3], 11, v[2:3]
	v_lshlrev_b32_e32 v0, 6, v0
	v_or_b32_e32 v129, v1, v131
	v_lshl_add_u64 v[2:3], s[86:87], 0, v[2:3]
	v_ashrrev_i32_e32 v1, 31, v0
	v_lshl_add_u64 v[108:109], v[0:1], 1, v[2:3]
	v_or_b32_e32 v0, v129, v111
	v_mad_u32_u24 v133, v0, s75, v99
	v_or_b32_e32 v132, v4, v131
	v_cmp_ne_u32_e32 vcc, 0, v4
	ds_read_b128 v[160:163], v133
	ds_read_b128 v[164:167], v133 offset:32
	ds_read_b128 v[168:171], v133 offset:64
	ds_read_b128 v[172:175], v133 offset:96
	ds_read_b128 v[176:179], v133 offset:4608
	ds_read_b128 v[180:183], v133 offset:4640
	ds_read_b128 v[184:187], v133 offset:4672
	ds_read_b128 v[188:191], v133 offset:4704
	ds_read_b128 v[192:195], v133 offset:9216
	ds_read_b128 v[196:199], v133 offset:9248
	ds_read_b128 v[200:203], v133 offset:9280
	ds_read_b128 v[204:207], v133 offset:9312
	ds_read_b128 v[208:211], v133 offset:13824
	ds_read_b128 v[212:215], v133 offset:13856
	ds_read_b128 v[216:219], v133 offset:13888
	ds_read_b128 v[220:223], v133 offset:13920
	ds_read_b128 v[224:227], v133 offset:18432
	ds_read_b128 v[228:231], v133 offset:18464
	ds_read_b128 v[232:235], v133 offset:18496
	ds_read_b128 v[236:239], v133 offset:18528
	s_and_b64 s[70:71], s[4:5], vcc
	s_waitcnt vmcnt(12) lgkmcnt(15)
	v_mfma_f32_32x32x16_bf16 v[48:63], v[160:163], v[92:95], 0
	s_waitcnt vmcnt(0)
	v_mul_f32_e32 v130, 0x3fb8aa3b, v128
	v_add_u32_e32 v126, 8, v126
	s_waitcnt lgkmcnt(15)
	v_mfma_f32_32x32x16_bf16 v[48:63], v[164:167], v[88:91], v[48:63]
	s_waitcnt lgkmcnt(15)
	v_mfma_f32_32x32x16_bf16 v[48:63], v[168:171], v[84:87], v[48:63]
	s_waitcnt lgkmcnt(15)
	v_mfma_f32_32x32x16_bf16 v[48:63], v[172:175], v[80:83], v[48:63]
	s_waitcnt lgkmcnt(15)
	v_mfma_f32_32x32x16_bf16 v[64:79], v[176:179], v[92:95], 0
	s_waitcnt lgkmcnt(14)
	v_mfma_f32_32x32x16_bf16 v[64:79], v[180:183], v[88:91], v[64:79]
	s_waitcnt lgkmcnt(13)
	v_mfma_f32_32x32x16_bf16 v[64:79], v[184:187], v[84:87], v[64:79]
	s_waitcnt lgkmcnt(12)
	v_mfma_f32_32x32x16_bf16 v[64:79], v[188:191], v[80:83], v[64:79]
	s_waitcnt lgkmcnt(11)
	v_mfma_f32_32x32x16_bf16 v[32:47], v[192:195], v[92:95], 0
	s_waitcnt lgkmcnt(10)
	v_mfma_f32_32x32x16_bf16 v[32:47], v[196:199], v[88:91], v[32:47]
	s_waitcnt lgkmcnt(9)
	v_mfma_f32_32x32x16_bf16 v[32:47], v[200:203], v[84:87], v[32:47]
	s_waitcnt lgkmcnt(8)
	v_mfma_f32_32x32x16_bf16 v[32:47], v[204:207], v[80:83], v[32:47]
	s_waitcnt lgkmcnt(7)
	v_mfma_f32_32x32x16_bf16 v[0:15], v[208:211], v[92:95], 0
	s_waitcnt lgkmcnt(6)
	v_mfma_f32_32x32x16_bf16 v[0:15], v[212:215], v[88:91], v[0:15]
	s_waitcnt lgkmcnt(5)
	v_mfma_f32_32x32x16_bf16 v[0:15], v[216:219], v[84:87], v[0:15]
	s_waitcnt lgkmcnt(4)
	v_mfma_f32_32x32x16_bf16 v[0:15], v[220:223], v[80:83], v[0:15]
	s_waitcnt lgkmcnt(3)
	v_mfma_f32_32x32x16_bf16 v[16:31], v[224:227], v[92:95], 0
	s_waitcnt lgkmcnt(2)
	v_mfma_f32_32x32x16_bf16 v[16:31], v[228:231], v[88:91], v[16:31]
	s_waitcnt lgkmcnt(1)
	v_mfma_f32_32x32x16_bf16 v[16:31], v[232:235], v[84:87], v[16:31]
	s_waitcnt lgkmcnt(0)
	v_mfma_f32_32x32x16_bf16 v[16:31], v[236:239], v[80:83], v[16:31]
	v_lshl_add_u32 v240, v129, 1, v110
	v_add_u32_e32 v241, v240, v119
	v_add_u32_e32 v240, v240, v97
	v_add_u32_e32 v240, 0xd800, v240
	v_add_u32_e32 v241, 0xd800, v241
	ds_read2_b64 v[160:163], v240 offset1:2
	ds_read2_b64 v[164:167], v241 offset1:2
	ds_read2_b64 v[168:171], v240 offset0:4 offset1:6
	ds_read2_b64 v[172:175], v241 offset0:4 offset1:6
	ds_read2_b64 v[176:179], v240 offset0:8 offset1:10
	ds_read2_b64 v[180:183], v241 offset0:8 offset1:10
	ds_read2_b64 v[184:187], v240 offset0:12 offset1:14
	ds_read2_b64 v[188:191], v241 offset0:12 offset1:14
	ds_read2_b64 v[192:195], v240 offset0:16 offset1:18
	ds_read2_b64 v[196:199], v241 offset0:16 offset1:18
	ds_read2_b64 v[200:203], v240 offset0:20 offset1:22
	ds_read2_b64 v[204:207], v241 offset0:20 offset1:22
	ds_read2_b64 v[208:211], v240 offset0:24 offset1:26
	ds_read2_b64 v[212:215], v241 offset0:24 offset1:26
	ds_read2_b64 v[216:219], v240 offset0:28 offset1:30
	ds_read2_b64 v[220:223], v241 offset0:28 offset1:30
	ds_read2_b64 v[224:227], v240 offset0:32 offset1:34
	ds_read2_b64 v[228:231], v241 offset0:32 offset1:34
	ds_read2_b64 v[232:235], v240 offset0:36 offset1:38
	ds_read2_b64 v[236:239], v241 offset0:36 offset1:38
	v_cndmask_b32_e64 v80, v125, v48, s[70:71]
	s_and_b64 s[70:71], s[6:7], vcc
	v_cndmask_b32_e64 v81, v125, v49, s[70:71]
	s_mov_b32 s70, 0xff800000
	v_max3_f32 v48, v80, s70, v81
	s_and_b64 s[70:71], s[8:9], vcc
	v_cndmask_b32_e64 v82, v125, v50, s[70:71]
	s_and_b64 s[70:71], s[10:11], vcc
	v_cndmask_b32_e64 v83, v125, v51, s[70:71]
	s_and_b64 s[70:71], s[12:13], vcc
	v_cndmask_b32_e64 v84, v125, v52, s[70:71]
	s_and_b64 s[70:71], s[14:15], vcc
	v_cndmask_b32_e64 v85, v125, v53, s[70:71]
	s_and_b64 s[70:71], s[16:17], vcc
	v_cndmask_b32_e64 v54, v125, v54, s[70:71]
	s_and_b64 s[70:71], s[18:19], vcc
	v_cndmask_b32_e64 v55, v125, v55, s[70:71]
	s_and_b64 s[70:71], s[20:21], vcc
	v_cndmask_b32_e64 v56, v125, v56, s[70:71]
	s_and_b64 s[70:71], s[22:23], vcc
	v_cndmask_b32_e64 v57, v125, v57, s[70:71]
	s_and_b64 s[70:71], s[24:25], vcc
	v_cndmask_b32_e64 v58, v125, v58, s[70:71]
	s_and_b64 s[70:71], s[26:27], vcc
	v_cndmask_b32_e64 v59, v125, v59, s[70:71]
	s_and_b64 s[70:71], s[28:29], vcc
	v_max3_f32 v48, v48, v82, v83
	v_cndmask_b32_e64 v60, v125, v60, s[70:71]
	s_and_b64 s[70:71], s[30:31], vcc
	v_max3_f32 v48, v48, v84, v85
	v_cndmask_b32_e64 v61, v125, v61, s[70:71]
	s_and_b64 s[70:71], s[34:35], vcc
	v_max3_f32 v48, v48, v54, v55
	v_cndmask_b32_e64 v62, v125, v62, s[70:71]
	s_and_b64 s[70:71], s[36:37], vcc
	v_max3_f32 v48, v48, v56, v57
	v_cndmask_b32_e64 v63, v125, v63, s[70:71]
	s_movk_i32 s70, 0x60
	v_max3_f32 v48, v48, v58, v59
	v_cmp_eq_u32_e64 s[70:71], s70, v131
	v_max3_f32 v48, v48, v60, v61
	s_or_b64 s[70:71], vcc, s[70:71]
	v_max3_f32 v48, v48, v62, v63
	v_cndmask_b32_e64 v49, v125, v64, s[70:71]
	v_cndmask_b32_e64 v50, v125, v65, s[70:71]
	v_max3_f32 v48, v48, v49, v50
	v_cndmask_b32_e64 v51, v125, v66, s[70:71]
	v_cndmask_b32_e64 v52, v125, v67, s[70:71]
	v_max3_f32 v48, v48, v51, v52
	v_cndmask_b32_e64 v53, v125, v68, s[70:71]
	v_cndmask_b32_e64 v86, v125, v69, s[70:71]
	v_max3_f32 v48, v48, v53, v86
	v_cndmask_b32_e64 v87, v125, v70, s[70:71]
	v_cndmask_b32_e64 v88, v125, v71, s[70:71]
	v_max3_f32 v48, v48, v87, v88
	v_cndmask_b32_e64 v89, v125, v72, s[70:71]
	v_cndmask_b32_e64 v90, v125, v73, s[70:71]
	v_cndmask_b32_e64 v91, v125, v74, s[70:71]
	v_cndmask_b32_e64 v92, v125, v75, s[70:71]
	v_cndmask_b32_e64 v93, v125, v76, s[70:71]
	v_cndmask_b32_e64 v94, v125, v77, s[70:71]
	v_max3_f32 v48, v48, v89, v90
	v_cndmask_b32_e64 v77, v94, v77, s[70:71]
	v_cndmask_b32_e64 v95, v93, v76, s[70:71]
	v_cndmask_b32_e64 v75, v92, v75, s[70:71]
	v_cndmask_b32_e64 v74, v91, v74, s[70:71]
	v_cndmask_b32_e64 v73, v90, v73, s[70:71]
	v_cndmask_b32_e64 v72, v89, v72, s[70:71]
	v_cndmask_b32_e64 v71, v88, v71, s[70:71]
	v_cndmask_b32_e64 v87, v87, v70, s[70:71]
	v_cndmask_b32_e64 v86, v86, v69, s[70:71]
	v_cndmask_b32_e64 v68, v53, v68, s[70:71]
	v_cndmask_b32_e64 v67, v52, v67, s[70:71]
	v_cndmask_b32_e64 v76, v51, v66, s[70:71]
	v_cndmask_b32_e64 v65, v50, v65, s[70:71]
	v_cndmask_b32_e64 v64, v49, v64, s[70:71]
	v_cndmask_b32_e64 v89, v125, v78, s[70:71]
	s_movk_i32 s70, 0x44
	v_cmp_lt_u32_e64 s[70:71], s70, v131
	s_or_b64 s[70:71], vcc, s[70:71]
	v_max3_f32 v48, v48, v91, v92
	v_cndmask_b32_e64 v79, v125, v79, s[70:71]
	v_cmp_lt_u32_e64 s[70:71], 63, v131
	v_max3_f32 v48, v48, v93, v94
	s_or_b64 s[70:71], vcc, s[70:71]
	v_max3_f32 v48, v48, v89, v79
	v_cndmask_b32_e64 v49, v125, v32, s[70:71]
	v_cndmask_b32_e64 v51, v125, v33, s[70:71]
	v_max3_f32 v48, v48, v49, v51
	v_cndmask_b32_e64 v66, v125, v34, s[70:71]
	v_cndmask_b32_e64 v69, v125, v35, s[70:71]
	v_max3_f32 v48, v48, v66, v69
	v_cndmask_b32_e64 v70, v125, v36, s[70:71]
	v_cndmask_b32_e64 v78, v125, v37, s[70:71]
	v_max3_f32 v48, v48, v70, v78
	v_cndmask_b32_e64 v88, v125, v38, s[70:71]
	v_cndmask_b32_e64 v90, v125, v39, s[70:71]
	v_max3_f32 v48, v48, v88, v90
	v_cndmask_b32_e64 v91, v125, v40, s[70:71]
	v_cndmask_b32_e64 v92, v125, v41, s[70:71]
	v_max3_f32 v48, v48, v91, v92
	v_cndmask_b32_e64 v93, v125, v42, s[70:71]
	v_cndmask_b32_e64 v53, v125, v43, s[70:71]
	v_max3_f32 v48, v48, v93, v53
	v_cndmask_b32_e64 v52, v125, v44, s[70:71]
	v_cndmask_b32_e64 v50, v125, v45, s[70:71]
	v_max3_f32 v48, v48, v52, v50
	v_cndmask_b32_e64 v50, v50, v45, s[70:71]
	v_cndmask_b32_e64 v52, v52, v44, s[70:71]
	v_cndmask_b32_e64 v53, v53, v43, s[70:71]
	v_cndmask_b32_e64 v135, v93, v42, s[70:71]
	v_cndmask_b32_e64 v145, v92, v41, s[70:71]
	v_cndmask_b32_e64 v146, v91, v40, s[70:71]
	v_cndmask_b32_e64 v137, v90, v39, s[70:71]
	v_cndmask_b32_e64 v147, v88, v38, s[70:71]
	v_cndmask_b32_e64 v91, v78, v37, s[70:71]
	v_cndmask_b32_e64 v148, v70, v36, s[70:71]
	v_cndmask_b32_e64 v149, v69, v35, s[70:71]
	v_cndmask_b32_e64 v150, v66, v34, s[70:71]
	v_cndmask_b32_e64 v151, v51, v33, s[70:71]
	v_cndmask_b32_e64 v153, v49, v32, s[70:71]
	v_cndmask_b32_e64 v49, v125, v46, s[70:71]
	v_cmp_lt_u32_e64 s[70:71], 36, v131
	s_or_b64 vcc, vcc, s[70:71]
	v_cndmask_b32_e32 v47, v125, v47, vcc
	v_cmp_ne_u32_e32 vcc, 0, v132
	v_max3_f32 v32, v48, v49, v47
	s_mov_b32 s70, 0x3fb8aa3b
	v_cndmask_b32_e32 v36, v125, v0, vcc
	v_cndmask_b32_e32 v38, v125, v1, vcc
	v_max3_f32 v32, v32, v36, v38
	v_cndmask_b32_e32 v39, v125, v2, vcc
	v_cndmask_b32_e32 v41, v125, v3, vcc
	v_max3_f32 v32, v32, v39, v41
	v_cndmask_b32_e32 v42, v125, v4, vcc
	v_cndmask_b32_e32 v43, v125, v5, vcc
	v_max3_f32 v32, v32, v42, v43
	v_cndmask_b32_e32 v40, v125, v6, vcc
	v_cndmask_b32_e32 v37, v125, v7, vcc
	v_max3_f32 v32, v32, v40, v37
	v_cndmask_b32_e32 v35, v125, v8, vcc
	v_cndmask_b32_e32 v34, v125, v9, vcc
	v_max3_f32 v32, v32, v35, v34
	v_cndmask_b32_e32 v33, v125, v10, vcc
	v_cndmask_b32_e32 v44, v125, v11, vcc
	v_max3_f32 v32, v32, v33, v44
	v_cndmask_b32_e32 v45, v125, v12, vcc
	v_cndmask_b32_e32 v46, v125, v13, vcc
	v_max3_f32 v32, v32, v45, v46
	v_cndmask_b32_e32 v66, v125, v14, vcc
	v_cndmask_b32_e32 v11, v44, v11, vcc
	v_cndmask_b32_e32 v44, v125, v15, vcc
	v_cndmask_b32_e32 v13, v46, v13, vcc
	v_cndmask_b32_e32 v12, v45, v12, vcc
	v_cndmask_b32_e32 v45, v43, v5, vcc
	v_cndmask_b32_e32 v46, v42, v4, vcc
	v_cndmask_b32_e32 v154, v36, v0, vcc
	v_max3_f32 v0, v32, v66, v44
	v_cndmask_b32_e64 v43, v125, v16, s[38:39]
	v_cndmask_b32_e64 v42, v125, v17, s[40:41]
	v_cndmask_b32_e32 v48, v41, v3, vcc
	v_cndmask_b32_e32 v51, v39, v2, vcc
	v_max3_f32 v0, v0, v43, v42
	v_cndmask_b32_e64 v41, v125, v18, s[42:43]
	v_cndmask_b32_e64 v39, v125, v19, s[44:45]
	v_cndmask_b32_e32 v131, v38, v1, vcc
	v_max3_f32 v0, v0, v41, v39
	v_cndmask_b32_e64 v38, v125, v20, s[46:47]
	v_cndmask_b32_e64 v36, v125, v21, s[48:49]
	v_max3_f32 v0, v0, v38, v36
	v_cndmask_b32_e64 v21, v125, v22, s[50:51]
	v_cndmask_b32_e64 v20, v125, v23, s[52:53]
	v_max3_f32 v0, v0, v21, v20
	v_cndmask_b32_e64 v19, v125, v24, s[54:55]
	v_cndmask_b32_e64 v18, v125, v25, s[56:57]
	v_max3_f32 v0, v0, v19, v18
	v_cndmask_b32_e64 v17, v125, v26, s[58:59]
	v_cndmask_b32_e64 v16, v125, v27, s[60:61]
	v_cndmask_b32_e32 v33, v33, v10, vcc
	v_max3_f32 v0, v0, v17, v16
	v_cndmask_b32_e64 v15, v125, v28, s[62:63]
	v_cndmask_b32_e64 v10, v125, v29, s[64:65]
	v_cndmask_b32_e32 v34, v34, v9, vcc
	v_cndmask_b32_e32 v35, v35, v8, vcc
	v_max3_f32 v0, v0, v15, v10
	v_cndmask_b32_e64 v9, v125, v30, s[66:67]
	v_cndmask_b32_e64 v8, v125, v31, s[68:69]
	v_max3_f32 v0, v0, v9, v8
	ds_bpermute_b32 v1, v120, v0
	v_cndmask_b32_e32 v40, v40, v6, vcc
	v_cndmask_b32_e32 v37, v37, v7, vcc
	v_cndmask_b32_e32 v14, v66, v14, vcc
	s_waitcnt lgkmcnt(0)
	v_max3_f32 v32, v0, v1, v130
	v_sub_f32_e32 v0, v80, v32
	v_exp_f32_e32 v0, v0
	v_sub_f32_e32 v1, v81, v32
	v_exp_f32_e32 v1, v1
	v_sub_f32_e32 v23, v56, v32
	v_add_f32_e32 v2, 0, v0
	v_exp_f32_e32 v66, v23
	v_add_f32_e32 v3, v1, v2
	v_sub_f32_e32 v2, v82, v32
	v_exp_f32_e32 v2, v2
	v_sub_f32_e32 v23, v57, v32
	v_exp_f32_e32 v70, v23
	v_sub_f32_e32 v23, v58, v32
	v_add_f32_e32 v4, v2, v3
	v_sub_f32_e32 v3, v83, v32
	v_exp_f32_e32 v3, v3
	v_exp_f32_e32 v78, v23
	v_sub_f32_e32 v23, v59, v32
	v_sub_f32_e32 v12, v12, v32
	v_add_f32_e32 v5, v3, v4
	v_sub_f32_e32 v4, v84, v32
	v_exp_f32_e32 v4, v4
	v_exp_f32_e32 v84, v23
	v_sub_f32_e32 v23, v60, v32
	v_exp_f32_e32 v90, v23
	v_add_f32_e32 v6, v4, v5
	v_sub_f32_e32 v5, v85, v32
	v_exp_f32_e32 v5, v5
	v_sub_f32_e32 v23, v61, v32
	v_exp_f32_e32 v94, v23
	v_sub_f32_e32 v23, v62, v32
	v_add_f32_e32 v7, v5, v6
	v_sub_f32_e32 v6, v54, v32
	v_exp_f32_e32 v6, v6
	v_exp_f32_e32 v136, v23
	v_sub_f32_e32 v23, v63, v32
	v_exp_f32_e32 v143, v23
	v_add_f32_e32 v22, v6, v7
	v_sub_f32_e32 v7, v55, v32
	v_exp_f32_e32 v7, v7
	v_sub_f32_e32 v23, v64, v32
	v_exp_f32_e32 v63, v23
	v_sub_f32_e32 v23, v65, v32
	v_add_f32_e32 v22, v7, v22
	v_add_f32_e32 v22, v66, v22
	v_add_f32_e32 v22, v70, v22
	v_add_f32_e32 v22, v78, v22
	v_add_f32_e32 v22, v84, v22
	v_add_f32_e32 v22, v90, v22
	v_add_f32_e32 v22, v94, v22
	v_exp_f32_e32 v69, v23
	v_sub_f32_e32 v23, v76, v32
	v_add_f32_e32 v22, v136, v22
	v_exp_f32_e32 v76, v23
	v_sub_f32_e32 v23, v67, v32
	v_add_f32_e32 v22, v143, v22
	v_exp_f32_e32 v82, v23
	v_sub_f32_e32 v23, v68, v32
	v_add_f32_e32 v22, v63, v22
	v_exp_f32_e32 v88, v23
	v_sub_f32_e32 v23, v86, v32
	v_add_f32_e32 v22, v69, v22
	v_exp_f32_e32 v93, v23
	v_sub_f32_e32 v23, v87, v32
	v_add_f32_e32 v22, v76, v22
	v_exp_f32_e32 v134, v23
	v_sub_f32_e32 v23, v71, v32
	v_add_f32_e32 v22, v82, v22
	v_exp_f32_e32 v139, v23
	v_sub_f32_e32 v23, v72, v32
	v_add_f32_e32 v22, v88, v22
	v_exp_f32_e32 v61, v23
	v_sub_f32_e32 v23, v73, v32
	v_add_f32_e32 v22, v93, v22
	v_exp_f32_e32 v68, v23
	v_sub_f32_e32 v23, v74, v32
	v_add_f32_e32 v22, v134, v22
	v_exp_f32_e32 v74, v23
	v_sub_f32_e32 v23, v75, v32
	v_add_f32_e32 v22, v139, v22
	v_exp_f32_e32 v80, v23
	v_sub_f32_e32 v23, v95, v32
	v_add_f32_e32 v22, v61, v22
	v_exp_f32_e32 v86, v23
	v_sub_f32_e32 v23, v77, v32
	v_add_f32_e32 v22, v68, v22
	v_exp_f32_e32 v92, v23
	v_sub_f32_e32 v23, v89, v32
	v_add_f32_e32 v22, v74, v22
	v_exp_f32_e32 v133, v23
	v_sub_f32_e32 v23, v79, v32
	v_add_f32_e32 v22, v80, v22
	v_exp_f32_e32 v138, v23
	v_sub_f32_e32 v23, v153, v32
	v_add_f32_e32 v22, v86, v22
	v_exp_f32_e32 v59, v23
	v_sub_f32_e32 v23, v151, v32
	v_add_f32_e32 v22, v92, v22
	v_exp_f32_e32 v67, v23
	v_sub_f32_e32 v23, v150, v32
	v_add_f32_e32 v22, v133, v22
	v_exp_f32_e32 v73, v23
	v_sub_f32_e32 v23, v149, v32
	v_add_f32_e32 v22, v138, v22
	v_exp_f32_e32 v79, v23
	v_sub_f32_e32 v23, v148, v32
	v_add_f32_e32 v22, v59, v22
	v_exp_f32_e32 v85, v23
	v_sub_f32_e32 v23, v91, v32
	v_add_f32_e32 v22, v67, v22
	v_exp_f32_e32 v91, v23
	v_sub_f32_e32 v23, v147, v32
	v_add_f32_e32 v22, v73, v22
	v_exp_f32_e32 v132, v23
	v_sub_f32_e32 v23, v137, v32
	v_add_f32_e32 v22, v79, v22
	v_exp_f32_e32 v137, v23
	v_sub_f32_e32 v23, v146, v32
	v_add_f32_e32 v22, v85, v22
	v_exp_f32_e32 v57, v23
	v_sub_f32_e32 v23, v145, v32
	v_add_f32_e32 v22, v91, v22
	v_exp_f32_e32 v65, v23
	v_sub_f32_e32 v23, v135, v32
	v_add_f32_e32 v22, v132, v22
	v_exp_f32_e32 v72, v23
	v_sub_f32_e32 v23, v53, v32
	v_add_f32_e32 v22, v137, v22
	v_exp_f32_e32 v77, v23
	v_sub_f32_e32 v23, v52, v32
	v_add_f32_e32 v22, v57, v22
	v_exp_f32_e32 v83, v23
	v_sub_f32_e32 v23, v50, v32
	v_add_f32_e32 v22, v65, v22
	v_exp_f32_e32 v89, v23
	v_sub_f32_e32 v23, v49, v32
	v_add_f32_e32 v22, v72, v22
	v_exp_f32_e32 v130, v23
	v_sub_f32_e32 v23, v47, v32
	v_add_f32_e32 v22, v77, v22
	v_exp_f32_e32 v135, v23
	v_sub_f32_e32 v23, v154, v32
	v_add_f32_e32 v22, v83, v22
	v_exp_f32_e32 v55, v23
	v_sub_f32_e32 v23, v131, v32
	v_add_f32_e32 v22, v89, v22
	v_exp_f32_e32 v62, v23
	v_sub_f32_e32 v23, v51, v32
	v_add_f32_e32 v22, v130, v22
	v_exp_f32_e32 v71, v23
	v_sub_f32_e32 v23, v48, v32
	v_add_f32_e32 v22, v135, v22
	v_exp_f32_e32 v75, v23
	v_sub_f32_e32 v23, v46, v32
	v_add_f32_e32 v22, v55, v22
	v_exp_f32_e32 v81, v23
	v_sub_f32_e32 v23, v45, v32
	v_add_f32_e32 v22, v62, v22
	v_exp_f32_e32 v87, v23
	v_sub_f32_e32 v23, v40, v32
	v_add_f32_e32 v22, v71, v22
	v_exp_f32_e32 v95, v23
	v_sub_f32_e32 v23, v37, v32
	v_add_f32_e32 v22, v75, v22
	v_exp_f32_e32 v131, v23
	v_sub_f32_e32 v23, v35, v32
	v_exp_f32_e32 v56, v12
	v_sub_f32_e32 v12, v13, v32
	v_add_f32_e32 v22, v81, v22
	v_exp_f32_e32 v51, v23
	v_sub_f32_e32 v23, v34, v32
	v_exp_f32_e32 v58, v12
	v_sub_f32_e32 v12, v14, v32
	v_add_f32_e32 v22, v87, v22
	v_exp_f32_e32 v52, v23
	v_sub_f32_e32 v23, v33, v32
	v_exp_f32_e32 v60, v12
	v_sub_f32_e32 v12, v44, v32
	v_add_f32_e32 v22, v95, v22
	v_exp_f32_e32 v53, v23
	v_sub_f32_e32 v11, v11, v32
	v_exp_f32_e32 v64, v12
	v_sub_f32_e32 v12, v43, v32
	v_sub_f32_e32 v8, v8, v32
	v_add_f32_e32 v22, v131, v22
	v_exp_f32_e32 v54, v11
	v_exp_f32_e32 v43, v12
	v_sub_f32_e32 v12, v42, v32
	v_exp_f32_e32 v42, v8
	v_lshl_add_u32 v8, v129, 1, v110
	v_add_f32_e32 v22, v51, v22
	v_cvt_pk_bf16_f32 v0, v0, v1
	v_cvt_pk_bf16_f32 v1, v2, v3
	v_cvt_pk_bf16_f32 v2, v4, v5
	v_add_u32_e32 v4, v8, v97
	v_add_f32_e32 v22, v52, v22
	v_add_u32_e32 v145, 0xd800, v4
	v_add_f32_e32 v22, v53, v22
	v_exp_f32_e32 v44, v12
	v_sub_f32_e32 v12, v41, v32
	v_cvt_pk_bf16_f32 v3, v6, v7
	v_add_f32_e32 v11, v54, v22
	v_exp_f32_e32 v45, v12
	v_sub_f32_e32 v12, v39, v32
	v_add_f32_e32 v11, v56, v11
	v_exp_f32_e32 v46, v12
	v_sub_f32_e32 v12, v38, v32
	v_add_f32_e32 v11, v58, v11
	v_exp_f32_e32 v47, v12
	v_sub_f32_e32 v12, v36, v32
	v_add_f32_e32 v11, v60, v11
	v_exp_f32_e32 v48, v12
	v_sub_f32_e32 v12, v21, v32
	v_add_f32_e32 v11, v64, v11
	v_exp_f32_e32 v49, v12
	v_sub_f32_e32 v12, v20, v32
	v_add_f32_e32 v11, v43, v11
	v_exp_f32_e32 v50, v12
	v_sub_f32_e32 v12, v19, v32
	v_add_f32_e32 v11, v44, v11
	v_exp_f32_e32 v35, v12
	v_sub_f32_e32 v12, v18, v32
	v_add_f32_e32 v11, v45, v11
	v_exp_f32_e32 v36, v12
	v_sub_f32_e32 v12, v17, v32
	v_add_f32_e32 v11, v46, v11
	v_exp_f32_e32 v37, v12
	v_sub_f32_e32 v12, v16, v32
	s_waitcnt lgkmcnt(0)
	v_mfma_f32_32x32x16_bf16 v[16:31], v[160:163], v[0:3], 0
	v_add_u32_e32 v4, v8, v119
	v_add_f32_e32 v11, v47, v11
	v_add_u32_e32 v129, 0xd800, v4
	v_add_f32_e32 v11, v48, v11
	v_cvt_pk_bf16_f32 v146, v66, v70
	v_cvt_pk_bf16_f32 v147, v78, v84
	v_cvt_pk_bf16_f32 v148, v90, v94
	v_cvt_pk_bf16_f32 v149, v136, v143
	v_add_f32_e32 v11, v49, v11
	v_add_f32_e32 v11, v50, v11
	v_exp_f32_e32 v38, v12
	v_sub_f32_e32 v12, v15, v32
	v_add_f32_e32 v11, v35, v11
	v_exp_f32_e32 v39, v12
	v_sub_f32_e32 v10, v10, v32
	v_add_f32_e32 v11, v36, v11
	v_exp_f32_e32 v40, v10
	v_sub_f32_e32 v9, v9, v32
	v_add_f32_e32 v11, v37, v11
	v_exp_f32_e32 v41, v9
	v_add_f32_e32 v11, v38, v11
	v_add_f32_e32 v11, v39, v11
	v_add_f32_e32 v10, v40, v11
	v_add_f32_e32 v9, v41, v10
	s_waitcnt lgkmcnt(0)
	v_mfma_f32_32x32x16_bf16 v[16:31], v[168:171], v[146:149], v[16:31]
	v_add_f32_e32 v33, v42, v9
	ds_bpermute_b32 v34, v120, v33
	v_fma_f32 v32, v128, s70, -v32
	v_exp_f32_e32 v32, v32
	v_mov_b32_e32 v143, v141
	s_waitcnt lgkmcnt(0)
	v_add_f32_e32 v33, v33, v34
	v_mfma_f32_32x32x16_bf16 v[0:15], v[164:167], v[0:3], 0
	v_add_f32_e32 v34, v32, v33
	v_lshl_add_u64 v[32:33], v[106:107], 0, v[140:141]
	v_lshl_add_u64 v[32:33], v[32:33], 0, v[142:143]
	v_mfma_f32_32x32x16_bf16 v[0:15], v[172:175], v[146:149], v[0:15]
	v_cvt_pk_bf16_f32 v146, v63, v69
	v_cvt_pk_bf16_f32 v147, v76, v82
	v_cvt_pk_bf16_f32 v148, v88, v93
	v_cvt_pk_bf16_f32 v149, v134, v139
	s_waitcnt lgkmcnt(0)
	s_nop 0
	v_mfma_f32_32x32x16_bf16 v[16:31], v[176:179], v[146:149], v[16:31]
	s_waitcnt lgkmcnt(0)
	v_mfma_f32_32x32x16_bf16 v[0:15], v[180:183], v[146:149], v[0:15]
	v_cvt_pk_bf16_f32 v146, v61, v68
	v_cvt_pk_bf16_f32 v147, v74, v80
	v_cvt_pk_bf16_f32 v148, v86, v92
	v_cvt_pk_bf16_f32 v149, v133, v138
	s_waitcnt lgkmcnt(0)
	s_nop 0
	v_mfma_f32_32x32x16_bf16 v[16:31], v[184:187], v[146:149], v[16:31]
	v_cvt_pk_bf16_f32 v66, v59, v67
	v_cvt_pk_bf16_f32 v67, v73, v79
	v_cvt_pk_bf16_f32 v68, v85, v91
	v_cvt_pk_bf16_f32 v69, v132, v137
	s_waitcnt lgkmcnt(0)
	s_nop 0
	v_mfma_f32_32x32x16_bf16 v[16:31], v[192:195], v[66:69], v[16:31]
	v_mfma_f32_32x32x16_bf16 v[0:15], v[188:191], v[146:149], v[0:15]
	s_waitcnt lgkmcnt(0)
	v_mfma_f32_32x32x16_bf16 v[0:15], v[196:199], v[66:69], v[0:15]
	v_cvt_pk_bf16_f32 v66, v57, v65
	v_cvt_pk_bf16_f32 v67, v72, v77
	v_cvt_pk_bf16_f32 v68, v83, v89
	v_cvt_pk_bf16_f32 v69, v130, v135
	s_waitcnt lgkmcnt(0)
	s_nop 0
	v_mfma_f32_32x32x16_bf16 v[16:31], v[200:203], v[66:69], v[16:31]
	s_waitcnt lgkmcnt(0)
	v_mfma_f32_32x32x16_bf16 v[0:15], v[204:207], v[66:69], v[0:15]
	v_cvt_pk_bf16_f32 v66, v55, v62
	v_cvt_pk_bf16_f32 v67, v71, v75
	v_cvt_pk_bf16_f32 v68, v81, v87
	v_cvt_pk_bf16_f32 v69, v95, v131
	s_waitcnt lgkmcnt(0)
	s_nop 0
	v_mfma_f32_32x32x16_bf16 v[16:31], v[208:211], v[66:69], v[16:31]
	v_cvt_pk_bf16_f32 v52, v51, v52
	v_cvt_pk_bf16_f32 v53, v53, v54
	v_cvt_pk_bf16_f32 v54, v56, v58
	v_cvt_pk_bf16_f32 v55, v60, v64
	s_waitcnt lgkmcnt(0)
	s_nop 0
	v_mfma_f32_32x32x16_bf16 v[16:31], v[216:219], v[52:55], v[16:31]
	v_cvt_pk_bf16_f32 v44, v43, v44
	v_cvt_pk_bf16_f32 v45, v45, v46
	v_cvt_pk_bf16_f32 v46, v47, v48
	v_cvt_pk_bf16_f32 v47, v49, v50
	s_waitcnt lgkmcnt(0)
	s_nop 0
	v_mfma_f32_32x32x16_bf16 v[16:31], v[224:227], v[44:47], v[16:31]
	v_cvt_pk_bf16_f32 v36, v35, v36
	v_cvt_pk_bf16_f32 v37, v37, v38
	v_cvt_pk_bf16_f32 v38, v39, v40
	v_cvt_pk_bf16_f32 v39, v41, v42
	v_mov_b32_e32 v145, v141
	s_waitcnt lgkmcnt(0)
	v_mfma_f32_32x32x16_bf16 v[16:31], v[232:235], v[36:39], v[16:31]
	global_load_dwordx4 v[92:95], v[32:33], off
	global_load_dwordx4 v[88:91], v[32:33], off offset:32
	global_load_dwordx4 v[84:87], v[32:33], off offset:64
	global_load_dwordx4 v[80:83], v[32:33], off offset:96
	v_div_scale_f32 v32, s[70:71], v34, v34, 1.0
	v_rcp_f32_e32 v33, v32
	s_nop 0
	v_fma_f32 v35, -v32, v33, 1.0
	v_mfma_f32_32x32x16_bf16 v[0:15], v[212:215], v[66:69], v[0:15]
	v_fmac_f32_e32 v33, v35, v33
	v_div_scale_f32 v35, vcc, 1.0, v34, 1.0
	v_mfma_f32_32x32x16_bf16 v[0:15], v[220:223], v[52:55], v[0:15]
	v_mfma_f32_32x32x16_bf16 v[0:15], v[228:231], v[44:47], v[0:15]
	s_waitcnt lgkmcnt(0)
	v_mfma_f32_32x32x16_bf16 v[0:15], v[236:239], v[36:39], v[0:15]
	v_mul_f32_e32 v36, v35, v33
	v_fma_f32 v37, -v32, v36, v35
	v_fmac_f32_e32 v36, v37, v33
	v_fma_f32 v32, -v32, v36, v35
	v_div_fmas_f32 v32, v32, v33, v36
	v_div_fixup_f32 v34, v32, v34, 1.0
	v_mul_f32_e32 v16, v16, v34
	v_mul_f32_e32 v17, v17, v34
	v_lshl_add_u64 v[32:33], v[108:109], 0, v[140:141]
	v_cvt_pk_bf16_f32 v16, v16, v17
	v_mul_f32_e32 v17, v18, v34
	v_lshl_add_u64 v[32:33], v[32:33], 0, v[144:145]
	v_mul_f32_e32 v18, v19, v34
	v_cvt_pk_bf16_f32 v17, v17, v18
	global_store_dwordx2 v[32:33], v[16:17], off
	v_mul_f32_e32 v16, v20, v34
	v_mul_f32_e32 v17, v21, v34
	v_cvt_pk_bf16_f32 v16, v16, v17
	v_mul_f32_e32 v17, v22, v34
	v_mul_f32_e32 v18, v23, v34
	v_cvt_pk_bf16_f32 v17, v17, v18
	global_store_dwordx2 v[32:33], v[16:17], off offset:16
	v_mul_f32_e32 v16, v24, v34
	v_mul_f32_e32 v17, v25, v34
	v_cvt_pk_bf16_f32 v16, v16, v17
	v_mul_f32_e32 v17, v26, v34
	v_mul_f32_e32 v18, v27, v34
	v_cvt_pk_bf16_f32 v17, v17, v18
	global_store_dwordx2 v[32:33], v[16:17], off offset:32
	v_mul_f32_e32 v16, v28, v34
	v_mul_f32_e32 v17, v29, v34
	v_cvt_pk_bf16_f32 v16, v16, v17
	v_mul_f32_e32 v17, v30, v34
	v_mul_f32_e32 v0, v0, v34
	v_mul_f32_e32 v1, v1, v34
	v_mul_f32_e32 v18, v31, v34
	v_cvt_pk_bf16_f32 v17, v17, v18
	global_store_dwordx2 v[32:33], v[16:17], off offset:48
	v_cvt_pk_bf16_f32 v0, v0, v1
	v_mul_f32_e32 v1, v2, v34
	v_mul_f32_e32 v2, v3, v34
	v_cvt_pk_bf16_f32 v1, v1, v2
	global_store_dwordx2 v[32:33], v[0:1], off offset:64
	v_mul_f32_e32 v0, v4, v34
	v_mul_f32_e32 v1, v5, v34
	v_cvt_pk_bf16_f32 v0, v0, v1
	v_mul_f32_e32 v1, v6, v34
	v_mul_f32_e32 v2, v7, v34
	v_cvt_pk_bf16_f32 v1, v1, v2
	global_store_dwordx2 v[32:33], v[0:1], off offset:80
	v_mul_f32_e32 v0, v8, v34
	v_mul_f32_e32 v1, v9, v34
	v_cvt_pk_bf16_f32 v0, v0, v1
	v_mul_f32_e32 v1, v10, v34
	v_mul_f32_e32 v2, v11, v34
	v_cvt_pk_bf16_f32 v1, v1, v2
	global_store_dwordx2 v[32:33], v[0:1], off offset:96
	v_mul_f32_e32 v0, v12, v34
	v_mul_f32_e32 v1, v13, v34
	v_cvt_pk_bf16_f32 v0, v0, v1
	v_mul_f32_e32 v1, v14, v34
	v_mul_f32_e32 v2, v15, v34
	v_cvt_pk_bf16_f32 v1, v1, v2
	v_mov_b32_e32 v2, v127
	global_store_dwordx2 v[32:33], v[0:1], off offset:112
	s_andn2_b64 exec, exec, s[94:95]
	s_cbranch_execz .LBB0_1076
